# code placement: the 12 GEMM mainloop heads and the attention inner loop head aligned to 64 bytes
# speedup vs baseline: 1.0026x; 1.0026x over previous
; #define PG8_STAGE(bufoff, gbase, voff) do { _Pragma("unroll") for (int _i = 0; _i < 2; ++_i) \
;         __builtin_amdgcn_global_load_lds((const unsigned*)((const char*)(gbase) + (voff)[_i]), (PG8_LAS unsigned*)(lds + (bufoff) + ldsw + _i * 8192), 16, 0, 0); } while (0)
; #define PG8_LDA(dst, b, h) do { _Pragma("unroll") for (int m = 0; m < 4; ++m) _Pragma("unroll") for (int k = 0; k < 2; ++k) dst[m][k] = *(const PG8_LAS bf16x8*)(lds + PG8_SA(b, h) + aoff + m * 2048 + k * 1024); } while (0)
; #define PG8_LDB(dst, b, h) do { _Pragma("unroll") for (int n = 0; n < 2; ++n) _Pragma("unroll") for (int k = 0; k < 2; ++k) dst[n][k] = *(const PG8_LAS bf16x8*)(lds + PG8_SB(b, h) + boff + n * 2048 + k * 1024); } while (0)
; #define PG8_WAIT_V(n) asm volatile("s_waitcnt vmcnt(" #n ")" ::: "memory")
; #define PG8_WAIT_L(n) asm volatile("s_waitcnt lgkmcnt(" #n ")" ::: "memory")
; template <class Epi, class Sched, bool ALIGN_EPI = false, bool SP2 = false>
; __device__ __forceinline__ void gemm_phase(PG8_LAS unsigned char* lds, const Gemm g, const Sched& S, const Epi& E) {
;     ...
;         const bool has_next = S.next(ui + 1, nxt);
;         const char* nA = has_next ? (const char*)g.A + (size_t)nxt.pm * tstepA + (size_t)nxt.z * g.azs + (size_t)(nxt.k0 >> 6) * kstA : cA; const char* nB = has_next ? (const char*)g.Bt + (size_t)nxt.pn * tstepB + (size_t)nxt.z * g.bzs + (size_t)nxt.k0 * 2 : cB;
;         const int nt = cur.nt;
;         for (int t = 0; t < nt; t += 2) {
;             const bool last = (t == nt - 2);
;             const char* a1 = cA + (size_t)(t + 1) * kstA;
;             const char* a2 = last ? nA : cA + (size_t)(t + 2) * kstA; const char* b2 = last ? nB : cB + (size_t)(t + 2) * kstep;
;             const char* a3 = a2 + kstA; const char* b3 = b2 + kstep;
;             if (last && has_next) S.a_ready(nxt);
;             if constexpr (SP2) {
;             PG8_LDB(B0, 0, 0); PG8_LDB(B1, 0, 1); PG8_SCHED; PG8_LDA(At, 0, 0); PG8_STAGE(PG8_SA(1, 1), a1 + hstepA, voffA);
;             PG8_WAIT_V(8); PG8_WAIT_L(0); PG8_BAR; PG8_MMA(0, 0, At, B0); PG8_MMA(0, 1, At, B1); PG8_BAR; PG8_SCHED;
;             PG8_LDA(At, 0, 1); PG8_STAGE(PG8_SB(0, 0), b2, voffB); PG8_STAGE(PG8_SB(0, 1), b2 + hstepB, voffB); PG8_STAGE(PG8_SA(0, 0), a2, voffA);
;             PG8_WAIT_V(8); PG8_WAIT_L(0); PG8_BAR; PG8_MMA(1, 0, At, B0); PG8_MMA(1, 1, At, B1); PG8_BAR; PG8_SCHED;
.LBB0_299:
	s_ashr_i32 s43, s42, 31
	s_lshl_b64 s[4:5], s[42:43], 20
	v_readlane_b32 s12, v254, 41
	v_readlane_b32 s13, v254, 42
	s_add_u32 s46, s12, s4
	s_addc_u32 s47, s13, s5
	s_and_b64 s[4:5], s[34:35], exec
	s_cselect_b32 s4, s47, s51
	s_cselect_b32 s5, s46, s50
	s_ashr_i32 s41, s40, 31
	s_lshl_b64 s[12:13], s[40:41], 20
	v_readlane_b32 s14, v253, 24
	s_add_u32 s48, s14, s12
	v_readlane_b32 s12, v253, 25
	s_addc_u32 s49, s12, s13
	s_and_b64 s[12:13], s[34:35], exec
	s_cselect_b32 s12, s49, s57
	s_cselect_b32 s13, s48, s56
	s_add_u32 s50, s50, 0x80080
	s_addc_u32 s51, s51, 0
	s_add_u32 s41, s56, 0x100
	s_addc_u32 s43, s57, 0
	s_mov_b32 s61, -2
	ds_read_b128 v[156:159], v152
	ds_read_b128 v[160:163], v152 offset:1024
	ds_read_b128 v[164:167], v152 offset:2048
	ds_read_b128 v[168:171], v152 offset:3072
	ds_read_b128 v[172:175], v153
	ds_read_b128 v[176:179], v153 offset:1024
	ds_read_b128 v[180:183], v153 offset:2048
	ds_read_b128 v[186:189], v153 offset:3072
	s_add_u32 s56, s50, 0xfff80080
	s_addc_u32 s57, s51, -1
	s_cmp_eq_u32 s61, 28
	s_cselect_b32 s59, s4, s57
	s_cselect_b32 s58, s5, s56
	s_cselect_b32 s57, s12, s43
	s_cselect_b32 s56, s13, s41
	v_lshl_add_u64 v[222:223], s[50:51], 0, v[142:143]
	s_add_i32 m0, s6, 0xc000
	ds_read_b128 v[190:193], v154
	ds_read_b128 v[194:197], v154 offset:1024
	ds_read_b128 v[198:201], v154 offset:2048
	ds_read_b128 v[202:205], v154 offset:3072
	ds_read_b128 v[206:209], v154 offset:4096
	ds_read_b128 v[210:213], v154 offset:5120
	ds_read_b128 v[214:217], v154 offset:6144
	ds_read_b128 v[218:221], v154 offset:7168
	global_load_lds_dwordx4 v[222:223], off
	v_lshl_add_u64 v[222:223], s[50:51], 0, v[144:145]
	s_add_i32 m0, s6, 0xe000
	s_nop 0
	global_load_lds_dwordx4 v[222:223], off
	s_waitcnt vmcnt(8)
	s_waitcnt lgkmcnt(0)
	s_setprio 1
	s_barrier
	v_mfma_f32_16x16x32_bf16 v[124:127], v[156:159], v[190:193], 0
	v_mfma_f32_16x16x32_bf16 v[120:123], v[164:167], v[190:193], 0
	v_mfma_f32_16x16x32_bf16 v[108:111], v[156:159], v[198:201], 0
	v_mfma_f32_16x16x32_bf16 v[104:107], v[164:167], v[198:201], 0
	v_mfma_f32_16x16x32_bf16 v[92:95], v[156:159], v[206:209], 0
	v_mfma_f32_16x16x32_bf16 v[88:91], v[164:167], v[206:209], 0
	v_mfma_f32_16x16x32_bf16 v[76:79], v[156:159], v[214:217], 0
	v_mfma_f32_16x16x32_bf16 v[72:75], v[164:167], v[214:217], 0
	v_mfma_f32_16x16x32_bf16 v[124:127], v[160:163], v[194:197], v[124:127]
	v_mfma_f32_16x16x32_bf16 v[120:123], v[168:171], v[194:197], v[120:123]
	v_mfma_f32_16x16x32_bf16 v[108:111], v[160:163], v[202:205], v[108:111]
	v_mfma_f32_16x16x32_bf16 v[104:107], v[168:171], v[202:205], v[104:107]
	v_mfma_f32_16x16x32_bf16 v[92:95], v[160:163], v[210:213], v[92:95]
	v_mfma_f32_16x16x32_bf16 v[88:91], v[168:171], v[210:213], v[88:91]
	v_mfma_f32_16x16x32_bf16 v[76:79], v[160:163], v[218:221], v[76:79]
	v_mfma_f32_16x16x32_bf16 v[72:75], v[168:171], v[218:221], v[72:75]
	s_setprio 0
	s_setprio 1
	v_mfma_f32_16x16x32_bf16 v[116:119], v[172:175], v[190:193], 0
	v_mfma_f32_16x16x32_bf16 v[112:115], v[180:183], v[190:193], 0
	v_mfma_f32_16x16x32_bf16 v[100:103], v[172:175], v[198:201], 0
	v_mfma_f32_16x16x32_bf16 v[96:99], v[180:183], v[198:201], 0
	v_mfma_f32_16x16x32_bf16 v[84:87], v[172:175], v[206:209], 0
	v_mfma_f32_16x16x32_bf16 v[80:83], v[180:183], v[206:209], 0
	v_mfma_f32_16x16x32_bf16 v[68:71], v[172:175], v[214:217], 0
	v_mfma_f32_16x16x32_bf16 v[64:67], v[180:183], v[214:217], 0
	v_mfma_f32_16x16x32_bf16 v[116:119], v[176:179], v[194:197], v[116:119]
	v_mfma_f32_16x16x32_bf16 v[112:115], v[186:189], v[194:197], v[112:115]
	v_mfma_f32_16x16x32_bf16 v[100:103], v[176:179], v[202:205], v[100:103]
	v_mfma_f32_16x16x32_bf16 v[96:99], v[186:189], v[202:205], v[96:99]
	v_mfma_f32_16x16x32_bf16 v[84:87], v[176:179], v[210:213], v[84:87]
	v_mfma_f32_16x16x32_bf16 v[80:83], v[186:189], v[210:213], v[80:83]
	v_mfma_f32_16x16x32_bf16 v[68:71], v[176:179], v[218:221], v[68:71]
	v_mfma_f32_16x16x32_bf16 v[64:67], v[186:189], v[218:221], v[64:67]
	s_barrier
	s_setprio 0
	s_add_i32 s62, s53, s3
	v_lshl_add_u64 v[222:223], s[56:57], 0, v[130:131]
	s_mov_b32 m0, s62
	ds_read_b128 v[190:193], v154 offset:16384
	ds_read_b128 v[194:197], v154 offset:17408
	ds_read_b128 v[198:201], v154 offset:18432
	ds_read_b128 v[202:205], v154 offset:19456
	ds_read_b128 v[206:209], v154 offset:20480
	ds_read_b128 v[210:213], v154 offset:21504
	ds_read_b128 v[214:217], v154 offset:22528
	ds_read_b128 v[218:221], v154 offset:23552
	global_load_lds_dwordx4 v[222:223], off
	s_add_i32 m0, s62, 0x2000
	s_add_u32 s62, s56, 0x80000
	v_lshl_add_u64 v[224:225], s[56:57], 0, v[134:135]
	s_addc_u32 s63, s57, 0
	s_add_i32 s64, s55, s3
	global_load_lds_dwordx4 v[224:225], off
	v_lshl_add_u64 v[226:227], s[62:63], 0, v[130:131]
	s_mov_b32 m0, s64
	v_lshl_add_u64 v[228:229], s[58:59], 0, v[132:133]
	global_load_lds_dwordx4 v[226:227], off
	v_lshl_add_u64 v[226:227], s[62:63], 0, v[134:135]
	s_add_i32 m0, s64, 0x2000
	s_nop 0
	global_load_lds_dwordx4 v[226:227], off
	v_lshl_add_u64 v[226:227], s[58:59], 0, v[128:129]
	s_mov_b32 m0, s6
	s_nop 0
	global_load_lds_dwordx4 v[226:227], off
	s_mov_b32 m0, s7
	s_nop 0
	global_load_lds_dwordx4 v[228:229], off
	s_waitcnt vmcnt(8)
	s_waitcnt lgkmcnt(0)
	s_setprio 1
	s_barrier
; #define PG8_STAGE(bufoff, gbase, voff) do { _Pragma("unroll") for (int _i = 0; _i < 2; ++_i) \
;         __builtin_amdgcn_global_load_lds((const unsigned*)((const char*)(gbase) + (voff)[_i]), (PG8_LAS unsigned*)(lds + (bufoff) + ldsw + _i * 8192), 16, 0, 0); } while (0)
; #define PG8_LDA(dst, b, h) do { _Pragma("unroll") for (int m = 0; m < 4; ++m) _Pragma("unroll") for (int k = 0; k < 2; ++k) dst[m][k] = *(const PG8_LAS bf16x8*)(lds + PG8_SA(b, h) + aoff + m * 2048 + k * 1024); } while (0)
; #define PG8_LDB(dst, b, h) do { _Pragma("unroll") for (int n = 0; n < 2; ++n) _Pragma("unroll") for (int k = 0; k < 2; ++k) dst[n][k] = *(const PG8_LAS bf16x8*)(lds + PG8_SB(b, h) + boff + n * 2048 + k * 1024); } while (0)
; #define PG8_MMA(ai, bj, At, Bt) do { __builtin_amdgcn_s_setprio(1); _Pragma("unroll") for (int m = 0; m < 4; ++m) _Pragma("unroll") for (int n = 0; n < 2; ++n) _Pragma("unroll") for (int k = 0; k < 2; ++k) \
;         acc[ai][bj][m][n] = __builtin_amdgcn_mfma_f32_16x16x32_bf16(Bt[n][k], At[m][k], acc[ai][bj][m][n], 0, 0, 0); __builtin_amdgcn_s_setprio(0); } while (0)
; #define PG8_WAIT_V(n) asm volatile("s_waitcnt vmcnt(" #n ")" ::: "memory")
; #define PG8_WAIT_L(n) asm volatile("s_waitcnt lgkmcnt(" #n ")" ::: "memory")
; #define PG8_BAR __builtin_amdgcn_s_barrier()
; #define PG8_SCHED __builtin_amdgcn_sched_barrier(0)
; template <class Epi, class Sched, bool ALIGN_EPI = false, bool SP2 = false>
; __device__ __forceinline__ void gemm_phase(PG8_LAS unsigned char* lds, const Gemm g, const Sched& S, const Epi& E) {
;     ...
;             PG8_WAIT_V(8); PG8_WAIT_L(0); PG8_BAR; PG8_MMA(1, 0, At, B0); PG8_MMA(1, 1, At, B1); PG8_BAR; PG8_SCHED;
;             PG8_LDB(B0, 1, 0); PG8_LDB(B1, 1, 1); PG8_SCHED; PG8_LDA(At, 1, 0); PG8_STAGE(PG8_SA(0, 1), a2 + hstepA, voffA);
;             PG8_WAIT_V(8); PG8_WAIT_L(0); PG8_BAR; PG8_MMA(0, 0, At, B0); PG8_MMA(0, 1, At, B1); PG8_BAR; PG8_SCHED;
	v_mfma_f32_16x16x32_bf16 v[60:63], v[156:159], v[190:193], 0
	v_mfma_f32_16x16x32_bf16 v[56:59], v[164:167], v[190:193], 0
	v_mfma_f32_16x16x32_bf16 v[44:47], v[156:159], v[198:201], 0
	v_mfma_f32_16x16x32_bf16 v[40:43], v[164:167], v[198:201], 0
	v_mfma_f32_16x16x32_bf16 v[28:31], v[156:159], v[206:209], 0
	v_mfma_f32_16x16x32_bf16 v[24:27], v[164:167], v[206:209], 0
	v_mfma_f32_16x16x32_bf16 v[12:15], v[156:159], v[214:217], 0
	v_mfma_f32_16x16x32_bf16 v[8:11], v[164:167], v[214:217], 0
	v_mfma_f32_16x16x32_bf16 v[60:63], v[160:163], v[194:197], v[60:63]
	v_mfma_f32_16x16x32_bf16 v[56:59], v[168:171], v[194:197], v[56:59]
	v_mfma_f32_16x16x32_bf16 v[44:47], v[160:163], v[202:205], v[44:47]
	v_mfma_f32_16x16x32_bf16 v[40:43], v[168:171], v[202:205], v[40:43]
	v_mfma_f32_16x16x32_bf16 v[28:31], v[160:163], v[210:213], v[28:31]
	v_mfma_f32_16x16x32_bf16 v[24:27], v[168:171], v[210:213], v[24:27]
	v_mfma_f32_16x16x32_bf16 v[12:15], v[160:163], v[218:221], v[12:15]
	v_mfma_f32_16x16x32_bf16 v[8:11], v[168:171], v[218:221], v[8:11]
	s_setprio 0
	s_setprio 1
	v_mfma_f32_16x16x32_bf16 v[52:55], v[172:175], v[190:193], 0
	v_mfma_f32_16x16x32_bf16 v[48:51], v[180:183], v[190:193], 0
	v_mfma_f32_16x16x32_bf16 v[36:39], v[172:175], v[198:201], 0
	v_mfma_f32_16x16x32_bf16 v[32:35], v[180:183], v[198:201], 0
	v_mfma_f32_16x16x32_bf16 v[20:23], v[172:175], v[206:209], 0
	v_mfma_f32_16x16x32_bf16 v[16:19], v[180:183], v[206:209], 0
	v_mfma_f32_16x16x32_bf16 v[4:7], v[172:175], v[214:217], 0
	v_mfma_f32_16x16x32_bf16 v[0:3], v[180:183], v[214:217], 0
	v_mfma_f32_16x16x32_bf16 v[52:55], v[176:179], v[194:197], v[52:55]
	v_mfma_f32_16x16x32_bf16 v[48:51], v[186:189], v[194:197], v[48:51]
	v_mfma_f32_16x16x32_bf16 v[36:39], v[176:179], v[202:205], v[36:39]
	v_mfma_f32_16x16x32_bf16 v[32:35], v[186:189], v[202:205], v[32:35]
	v_mfma_f32_16x16x32_bf16 v[20:23], v[176:179], v[210:213], v[20:23]
	v_mfma_f32_16x16x32_bf16 v[16:19], v[186:189], v[210:213], v[16:19]
	v_mfma_f32_16x16x32_bf16 v[4:7], v[176:179], v[218:221], v[4:7]
	v_mfma_f32_16x16x32_bf16 v[0:3], v[186:189], v[218:221], v[0:3]
	s_barrier
	s_setprio 0
	s_add_i32 s62, 0, 0x18000
	v_add_u32_e32 v155, s62, v150
	s_add_i32 s63, 0, 0x1c000
	ds_read_b128 v[156:159], v155
	ds_read_b128 v[160:163], v155 offset:1024
	ds_read_b128 v[164:167], v155 offset:2048
	ds_read_b128 v[168:171], v155 offset:3072
	v_add_u32_e32 v155, s63, v150
	ds_read_b128 v[172:175], v155
	ds_read_b128 v[176:179], v155 offset:1024
	ds_read_b128 v[180:183], v155 offset:2048
	ds_read_b128 v[186:189], v155 offset:3072
	s_add_u32 s58, s58, 0x80000
	s_addc_u32 s59, s59, 0
	s_mov_b32 m0, s8
	v_lshl_add_u64 v[230:231], s[58:59], 0, v[128:129]
	ds_read_b128 v[190:193], v154 offset:32768
	ds_read_b128 v[194:197], v154 offset:33792
	ds_read_b128 v[198:201], v154 offset:34816
	ds_read_b128 v[202:205], v154 offset:35840
	ds_read_b128 v[206:209], v154 offset:36864
	ds_read_b128 v[210:213], v154 offset:37888
	ds_read_b128 v[214:217], v154 offset:38912
	ds_read_b128 v[218:221], v154 offset:39936
	global_load_lds_dwordx4 v[230:231], off
	v_lshl_add_u64 v[230:231], s[58:59], 0, v[132:133]
	s_mov_b32 m0, s9
	s_nop 0
	global_load_lds_dwordx4 v[230:231], off
	s_waitcnt vmcnt(8)
	s_waitcnt lgkmcnt(0)
	s_setprio 1
	s_barrier
	v_mfma_f32_16x16x32_bf16 v[124:127], v[156:159], v[190:193], v[124:127]
	v_mfma_f32_16x16x32_bf16 v[120:123], v[164:167], v[190:193], v[120:123]
	v_mfma_f32_16x16x32_bf16 v[108:111], v[156:159], v[198:201], v[108:111]
	v_mfma_f32_16x16x32_bf16 v[104:107], v[164:167], v[198:201], v[104:107]
	v_mfma_f32_16x16x32_bf16 v[92:95], v[156:159], v[206:209], v[92:95]
	v_mfma_f32_16x16x32_bf16 v[88:91], v[164:167], v[206:209], v[88:91]
	v_mfma_f32_16x16x32_bf16 v[76:79], v[156:159], v[214:217], v[76:79]
	v_mfma_f32_16x16x32_bf16 v[72:75], v[164:167], v[214:217], v[72:75]
	v_mfma_f32_16x16x32_bf16 v[124:127], v[160:163], v[194:197], v[124:127]
	v_mfma_f32_16x16x32_bf16 v[120:123], v[168:171], v[194:197], v[120:123]
	v_mfma_f32_16x16x32_bf16 v[108:111], v[160:163], v[202:205], v[108:111]
	v_mfma_f32_16x16x32_bf16 v[104:107], v[168:171], v[202:205], v[104:107]
	v_mfma_f32_16x16x32_bf16 v[92:95], v[160:163], v[210:213], v[92:95]
	v_mfma_f32_16x16x32_bf16 v[88:91], v[168:171], v[210:213], v[88:91]
	v_mfma_f32_16x16x32_bf16 v[76:79], v[160:163], v[218:221], v[76:79]
	v_mfma_f32_16x16x32_bf16 v[72:75], v[168:171], v[218:221], v[72:75]
	s_setprio 0
	s_setprio 1
	v_mfma_f32_16x16x32_bf16 v[116:119], v[172:175], v[190:193], v[116:119]
	v_mfma_f32_16x16x32_bf16 v[112:115], v[180:183], v[190:193], v[112:115]
	v_mfma_f32_16x16x32_bf16 v[100:103], v[172:175], v[198:201], v[100:103]
	v_mfma_f32_16x16x32_bf16 v[96:99], v[180:183], v[198:201], v[96:99]
	v_mfma_f32_16x16x32_bf16 v[84:87], v[172:175], v[206:209], v[84:87]
	v_mfma_f32_16x16x32_bf16 v[80:83], v[180:183], v[206:209], v[80:83]
	v_mfma_f32_16x16x32_bf16 v[68:71], v[172:175], v[214:217], v[68:71]
	v_mfma_f32_16x16x32_bf16 v[64:67], v[180:183], v[214:217], v[64:67]
	v_mfma_f32_16x16x32_bf16 v[116:119], v[176:179], v[194:197], v[116:119]
	v_mfma_f32_16x16x32_bf16 v[112:115], v[186:189], v[194:197], v[112:115]
	v_mfma_f32_16x16x32_bf16 v[100:103], v[176:179], v[202:205], v[100:103]
	v_mfma_f32_16x16x32_bf16 v[96:99], v[186:189], v[202:205], v[96:99]
	v_mfma_f32_16x16x32_bf16 v[84:87], v[176:179], v[210:213], v[84:87]
	v_mfma_f32_16x16x32_bf16 v[80:83], v[186:189], v[210:213], v[80:83]
	v_mfma_f32_16x16x32_bf16 v[68:71], v[176:179], v[218:221], v[68:71]
	v_mfma_f32_16x16x32_bf16 v[64:67], v[186:189], v[218:221], v[64:67]
	s_barrier
; #define PG8_STAGE(bufoff, gbase, voff) do { _Pragma("unroll") for (int _i = 0; _i < 2; ++_i) \
;         __builtin_amdgcn_global_load_lds((const unsigned*)((const char*)(gbase) + (voff)[_i]), (PG8_LAS unsigned*)(lds + (bufoff) + ldsw + _i * 8192), 16, 0, 0); } while (0)
; #define PG8_LDA(dst, b, h) do { _Pragma("unroll") for (int m = 0; m < 4; ++m) _Pragma("unroll") for (int k = 0; k < 2; ++k) dst[m][k] = *(const PG8_LAS bf16x8*)(lds + PG8_SA(b, h) + aoff + m * 2048 + k * 1024); } while (0)
; #define PG8_MMA(ai, bj, At, Bt) do { __builtin_amdgcn_s_setprio(1); _Pragma("unroll") for (int m = 0; m < 4; ++m) _Pragma("unroll") for (int n = 0; n < 2; ++n) _Pragma("unroll") for (int k = 0; k < 2; ++k) \
;         acc[ai][bj][m][n] = __builtin_amdgcn_mfma_f32_16x16x32_bf16(Bt[n][k], At[m][k], acc[ai][bj][m][n], 0, 0, 0); __builtin_amdgcn_s_setprio(0); } while (0)
; #define PG8_WAIT_V(n) asm volatile("s_waitcnt vmcnt(" #n ")" ::: "memory")
; #define PG8_WAIT_L(n) asm volatile("s_waitcnt lgkmcnt(" #n ")" ::: "memory")
; #define PG8_BAR __builtin_amdgcn_s_barrier()
; #define PG8_SCHED __builtin_amdgcn_sched_barrier(0)
; template <class Epi, class Sched, bool ALIGN_EPI = false, bool SP2 = false>
; __device__ __forceinline__ void gemm_phase(PG8_LAS unsigned char* lds, const Gemm g, const Sched& S, const Epi& E) {
;     ...
;             PG8_LDA(At, 1, 1); PG8_STAGE(PG8_SB(1, 0), b3, voffB); PG8_STAGE(PG8_SB(1, 1), b3 + hstepB, voffB); PG8_STAGE(PG8_SA(1, 0), a3, voffA);
;             PG8_WAIT_V(8); PG8_WAIT_L(0); PG8_BAR; PG8_MMA(1, 0, At, B0); PG8_MMA(1, 1, At, B1); PG8_BAR; PG8_SCHED;
	s_setprio 0
	s_add_i32 s58, s62, s3
	v_lshl_add_u64 v[222:223], v[222:223], 0, s[36:37]
	s_mov_b32 m0, s58
	ds_read_b128 v[190:193], v154 offset:49152
	ds_read_b128 v[194:197], v154 offset:50176
	ds_read_b128 v[198:201], v154 offset:51200
	ds_read_b128 v[202:205], v154 offset:52224
	ds_read_b128 v[206:209], v154 offset:53248
	ds_read_b128 v[210:213], v154 offset:54272
	ds_read_b128 v[214:217], v154 offset:55296
	ds_read_b128 v[218:221], v154 offset:56320
	global_load_lds_dwordx4 v[222:223], off
	s_add_i32 m0, s58, 0x2000
	s_add_u32 s56, s56, 0x80080
	v_lshl_add_u64 v[222:223], v[224:225], 0, s[36:37]
	s_addc_u32 s57, s57, 0
	s_add_i32 s58, s63, s3
	global_load_lds_dwordx4 v[222:223], off
	v_lshl_add_u64 v[222:223], s[56:57], 0, v[130:131]
	s_mov_b32 m0, s58
	s_nop 0
	global_load_lds_dwordx4 v[222:223], off
	v_lshl_add_u64 v[222:223], s[56:57], 0, v[134:135]
	s_add_i32 m0, s58, 0x2000
	s_nop 0
	global_load_lds_dwordx4 v[222:223], off
	v_lshl_add_u64 v[222:223], v[226:227], 0, s[36:37]
	s_mov_b32 m0, s44
	s_nop 0
	global_load_lds_dwordx4 v[222:223], off
	v_lshl_add_u64 v[222:223], v[228:229], 0, s[36:37]
	s_mov_b32 m0, s45
	s_nop 0
	global_load_lds_dwordx4 v[222:223], off
	s_waitcnt vmcnt(8)
	s_waitcnt lgkmcnt(0)
	s_setprio 1
	s_barrier
	v_mfma_f32_16x16x32_bf16 v[60:63], v[156:159], v[190:193], v[60:63]
	v_mfma_f32_16x16x32_bf16 v[56:59], v[164:167], v[190:193], v[56:59]
	v_mfma_f32_16x16x32_bf16 v[44:47], v[156:159], v[198:201], v[44:47]
	v_mfma_f32_16x16x32_bf16 v[40:43], v[164:167], v[198:201], v[40:43]
	v_mfma_f32_16x16x32_bf16 v[28:31], v[156:159], v[206:209], v[28:31]
	v_mfma_f32_16x16x32_bf16 v[24:27], v[164:167], v[206:209], v[24:27]
	v_mfma_f32_16x16x32_bf16 v[12:15], v[156:159], v[214:217], v[12:15]
	v_mfma_f32_16x16x32_bf16 v[8:11], v[164:167], v[214:217], v[8:11]
	v_mfma_f32_16x16x32_bf16 v[60:63], v[160:163], v[194:197], v[60:63]
	v_mfma_f32_16x16x32_bf16 v[56:59], v[168:171], v[194:197], v[56:59]
	v_mfma_f32_16x16x32_bf16 v[44:47], v[160:163], v[202:205], v[44:47]
	v_mfma_f32_16x16x32_bf16 v[40:43], v[168:171], v[202:205], v[40:43]
	v_mfma_f32_16x16x32_bf16 v[28:31], v[160:163], v[210:213], v[28:31]
	v_mfma_f32_16x16x32_bf16 v[24:27], v[168:171], v[210:213], v[24:27]
	v_mfma_f32_16x16x32_bf16 v[12:15], v[160:163], v[218:221], v[12:15]
	v_mfma_f32_16x16x32_bf16 v[8:11], v[168:171], v[218:221], v[8:11]
	s_setprio 0
	s_setprio 1
	v_mfma_f32_16x16x32_bf16 v[52:55], v[172:175], v[190:193], v[52:55]
	v_mfma_f32_16x16x32_bf16 v[48:51], v[180:183], v[190:193], v[48:51]
	v_mfma_f32_16x16x32_bf16 v[36:39], v[172:175], v[198:201], v[36:39]
	v_mfma_f32_16x16x32_bf16 v[32:35], v[180:183], v[198:201], v[32:35]
	v_mfma_f32_16x16x32_bf16 v[20:23], v[172:175], v[206:209], v[20:23]
	v_mfma_f32_16x16x32_bf16 v[16:19], v[180:183], v[206:209], v[16:19]
	v_mfma_f32_16x16x32_bf16 v[4:7], v[172:175], v[214:217], v[4:7]
	v_mfma_f32_16x16x32_bf16 v[0:3], v[180:183], v[214:217], v[0:3]
	v_mfma_f32_16x16x32_bf16 v[52:55], v[176:179], v[194:197], v[52:55]
	v_mfma_f32_16x16x32_bf16 v[48:51], v[186:189], v[194:197], v[48:51]
	v_mfma_f32_16x16x32_bf16 v[36:39], v[176:179], v[202:205], v[36:39]
	v_mfma_f32_16x16x32_bf16 v[32:35], v[186:189], v[202:205], v[32:35]
	v_mfma_f32_16x16x32_bf16 v[20:23], v[176:179], v[210:213], v[20:23]
	v_mfma_f32_16x16x32_bf16 v[16:19], v[186:189], v[210:213], v[16:19]
	v_mfma_f32_16x16x32_bf16 v[4:7], v[176:179], v[218:221], v[4:7]
	v_mfma_f32_16x16x32_bf16 v[0:3], v[186:189], v[218:221], v[0:3]
	s_barrier
	s_setprio 0
	s_add_i32 s61, s61, 2
	s_add_u32 s50, s50, 0x100
	s_addc_u32 s51, s51, 0
	s_add_u32 s41, s41, 0x100
	s_addc_u32 s43, s43, 0
	s_cmp_gt_u32 s61, 29
	s_cbranch_scc1 .Lmy_peel_0_exit
	.p2alignl 6, 3212836864

;     __device__ __forceinline__ void a_ready(const Unit& u) const {
;     ...
;         }
;         asm volatile("" ::: "memory"); __builtin_amdgcn_s_barrier(); asm volatile("" ::: "memory");
.LBB0_396:
	s_or_b64 exec, exec, s[52:53]
	s_barrier
	.p2alignl 6, 3212836864

; #define PG8_STAGE(bufoff, gbase, voff) do { _Pragma("unroll") for (int _i = 0; _i < 2; ++_i) \
;         __builtin_amdgcn_global_load_lds((const unsigned*)((const char*)(gbase) + (voff)[_i]), (PG8_LAS unsigned*)(lds + (bufoff) + ldsw + _i * 8192), 16, 0, 0); } while (0)
; #define PG8_LDA(dst, b, h) do { _Pragma("unroll") for (int m = 0; m < 4; ++m) _Pragma("unroll") for (int k = 0; k < 2; ++k) dst[m][k] = *(const PG8_LAS bf16x8*)(lds + PG8_SA(b, h) + aoff + m * 2048 + k * 1024); } while (0)
; #define PG8_LDB(dst, b, h) do { _Pragma("unroll") for (int n = 0; n < 2; ++n) _Pragma("unroll") for (int k = 0; k < 2; ++k) dst[n][k] = *(const PG8_LAS bf16x8*)(lds + PG8_SB(b, h) + boff + n * 2048 + k * 1024); } while (0)
; #define PG8_MMA(ai, bj, At, Bt) do { __builtin_amdgcn_s_setprio(1); _Pragma("unroll") for (int m = 0; m < 4; ++m) _Pragma("unroll") for (int n = 0; n < 2; ++n) _Pragma("unroll") for (int k = 0; k < 2; ++k) \
;         acc[ai][bj][m][n] = __builtin_amdgcn_mfma_f32_16x16x32_bf16(Bt[n][k], At[m][k], acc[ai][bj][m][n], 0, 0, 0); __builtin_amdgcn_s_setprio(0); } while (0)
; #define PG8_WAIT_V(n) asm volatile("s_waitcnt vmcnt(" #n ")" ::: "memory")
; #define PG8_WAIT_L(n) asm volatile("s_waitcnt lgkmcnt(" #n ")" ::: "memory")
; #define PG8_BAR __builtin_amdgcn_s_barrier()
; #define PG8_SCHED __builtin_amdgcn_sched_barrier(0)
; template <class Epi, class Sched, bool ALIGN_EPI = false, bool SP2 = false>
; __device__ __forceinline__ void gemm_phase(PG8_LAS unsigned char* lds, const Gemm g, const Sched& S, const Epi& E) {
;     ...
;             PG8_LDB(B0, 0, 0); PG8_LDB(B1, 0, 1); PG8_SCHED; PG8_LDA(At, 0, 0); PG8_STAGE(PG8_SA(1, 1), a1 + hstepA, voffA);
;             PG8_WAIT_V(8); PG8_WAIT_L(0); PG8_BAR; PG8_MMA(0, 0, At, B0); PG8_MMA(0, 1, At, B1); PG8_BAR; PG8_SCHED;
;             PG8_LDA(At, 0, 1); PG8_STAGE(PG8_SB(0, 0), b2, voffB); PG8_STAGE(PG8_SB(0, 1), b2 + hstepB, voffB); PG8_STAGE(PG8_SA(0, 0), a2, voffA);
;             PG8_WAIT_V(8); PG8_WAIT_L(0); PG8_BAR; PG8_MMA(1, 0, At, B0); PG8_MMA(1, 1, At, B1); PG8_BAR; PG8_SCHED;
.LBB0_655:
	s_add_u32 s50, s50, 0x80080
	s_addc_u32 s51, s51, 0
	s_add_u32 s4, s52, 0x100
	s_addc_u32 s5, s53, 0
	s_mov_b32 s46, -2
	ds_read_b128 v[166:169], v163
	ds_read_b128 v[170:173], v163 offset:1024
	ds_read_b128 v[174:177], v163 offset:2048
	ds_read_b128 v[178:181], v163 offset:3072
	ds_read_b128 v[186:189], v164
	ds_read_b128 v[190:193], v164 offset:1024
	ds_read_b128 v[194:197], v164 offset:2048
	ds_read_b128 v[198:201], v164 offset:3072
	s_add_u32 s47, s50, 0xfff80080
	s_addc_u32 s52, s51, -1
	s_cmp_eq_u32 s46, 28
	s_cselect_b32 s59, s63, s52
	s_cselect_b32 s58, s62, s47
	s_cselect_b32 s53, s65, s5
	s_cselect_b32 s52, s64, s4
	v_lshl_add_u64 v[158:159], s[50:51], 0, v[152:153]
	s_add_i32 m0, s9, 0xc000
	ds_read_b128 v[202:205], v165
	ds_read_b128 v[206:209], v165 offset:1024
	ds_read_b128 v[210:213], v165 offset:2048
	ds_read_b128 v[214:217], v165 offset:3072
	ds_read_b128 v[218:221], v165 offset:4096
	ds_read_b128 v[222:225], v165 offset:5120
	ds_read_b128 v[226:229], v165 offset:6144
	ds_read_b128 v[230:233], v165 offset:7168
	global_load_lds_dwordx4 v[158:159], off
	v_lshl_add_u64 v[158:159], s[50:51], 0, v[154:155]
	s_add_i32 m0, s9, 0xe000
	s_nop 0
	global_load_lds_dwordx4 v[158:159], off
	s_waitcnt vmcnt(8)
	s_waitcnt lgkmcnt(0)
	s_setprio 1
	s_barrier
	v_mfma_f32_16x16x32_bf16 v[124:127], v[166:169], v[202:205], 0
	v_mfma_f32_16x16x32_bf16 v[120:123], v[174:177], v[202:205], 0
	v_mfma_f32_16x16x32_bf16 v[112:115], v[166:169], v[210:213], 0
	v_mfma_f32_16x16x32_bf16 v[104:107], v[174:177], v[210:213], 0
	v_mfma_f32_16x16x32_bf16 v[96:99], v[166:169], v[218:221], 0
	v_mfma_f32_16x16x32_bf16 v[88:91], v[174:177], v[218:221], 0
	v_mfma_f32_16x16x32_bf16 v[80:83], v[166:169], v[226:229], 0
	v_mfma_f32_16x16x32_bf16 v[72:75], v[174:177], v[226:229], 0
	v_mfma_f32_16x16x32_bf16 v[124:127], v[170:173], v[206:209], v[124:127]
	v_mfma_f32_16x16x32_bf16 v[120:123], v[178:181], v[206:209], v[120:123]
	v_mfma_f32_16x16x32_bf16 v[112:115], v[170:173], v[214:217], v[112:115]
	v_mfma_f32_16x16x32_bf16 v[104:107], v[178:181], v[214:217], v[104:107]
	v_mfma_f32_16x16x32_bf16 v[96:99], v[170:173], v[222:225], v[96:99]
	v_mfma_f32_16x16x32_bf16 v[88:91], v[178:181], v[222:225], v[88:91]
	v_mfma_f32_16x16x32_bf16 v[80:83], v[170:173], v[230:233], v[80:83]
	v_mfma_f32_16x16x32_bf16 v[72:75], v[178:181], v[230:233], v[72:75]
	s_setprio 0
	s_setprio 1
	v_mfma_f32_16x16x32_bf16 v[116:119], v[186:189], v[202:205], 0
	v_mfma_f32_16x16x32_bf16 v[108:111], v[194:197], v[202:205], 0
	v_mfma_f32_16x16x32_bf16 v[100:103], v[186:189], v[210:213], 0
	v_mfma_f32_16x16x32_bf16 v[92:95], v[194:197], v[210:213], 0
	v_mfma_f32_16x16x32_bf16 v[84:87], v[186:189], v[218:221], 0
	v_mfma_f32_16x16x32_bf16 v[76:79], v[194:197], v[218:221], 0
	v_mfma_f32_16x16x32_bf16 v[68:71], v[186:189], v[226:229], 0
	v_mfma_f32_16x16x32_bf16 v[64:67], v[194:197], v[226:229], 0
	v_mfma_f32_16x16x32_bf16 v[116:119], v[190:193], v[206:209], v[116:119]
	v_mfma_f32_16x16x32_bf16 v[108:111], v[198:201], v[206:209], v[108:111]
	v_mfma_f32_16x16x32_bf16 v[100:103], v[190:193], v[214:217], v[100:103]
	v_mfma_f32_16x16x32_bf16 v[92:95], v[198:201], v[214:217], v[92:95]
	v_mfma_f32_16x16x32_bf16 v[84:87], v[190:193], v[222:225], v[84:87]
	v_mfma_f32_16x16x32_bf16 v[76:79], v[198:201], v[222:225], v[76:79]
	v_mfma_f32_16x16x32_bf16 v[68:71], v[190:193], v[230:233], v[68:71]
	v_mfma_f32_16x16x32_bf16 v[64:67], v[198:201], v[230:233], v[64:67]
	s_barrier
	s_setprio 0
	s_add_i32 s47, s44, s8
	v_lshl_add_u64 v[158:159], s[52:53], 0, v[130:131]
	s_mov_b32 m0, s47
	ds_read_b128 v[202:205], v165 offset:16384
	ds_read_b128 v[206:209], v165 offset:17408
	ds_read_b128 v[210:213], v165 offset:18432
	ds_read_b128 v[214:217], v165 offset:19456
	ds_read_b128 v[218:221], v165 offset:20480
	ds_read_b128 v[222:225], v165 offset:21504
	ds_read_b128 v[226:229], v165 offset:22528
	ds_read_b128 v[230:233], v165 offset:23552
	global_load_lds_dwordx4 v[158:159], off
	s_add_i32 m0, s47, 0x2000
	s_add_u32 s66, s52, 0x80000
	v_lshl_add_u64 v[182:183], s[52:53], 0, v[134:135]
	s_addc_u32 s67, s53, 0
	s_add_i32 s47, s45, s8
	global_load_lds_dwordx4 v[182:183], off
	v_lshl_add_u64 v[234:235], s[66:67], 0, v[130:131]
	s_mov_b32 m0, s47
	v_lshl_add_u64 v[236:237], s[58:59], 0, v[132:133]
	global_load_lds_dwordx4 v[234:235], off
	v_lshl_add_u64 v[234:235], s[66:67], 0, v[134:135]
	s_add_i32 m0, s47, 0x2000
	s_nop 0
	global_load_lds_dwordx4 v[234:235], off
	v_lshl_add_u64 v[234:235], s[58:59], 0, v[128:129]
	s_mov_b32 m0, s9
	s_nop 0
	global_load_lds_dwordx4 v[234:235], off
	s_mov_b32 m0, s10
	s_nop 0
	global_load_lds_dwordx4 v[236:237], off
	s_waitcnt vmcnt(8)
	s_waitcnt lgkmcnt(0)
	s_setprio 1
	s_barrier
; #define PG8_STAGE(bufoff, gbase, voff) do { _Pragma("unroll") for (int _i = 0; _i < 2; ++_i) \
;         __builtin_amdgcn_global_load_lds((const unsigned*)((const char*)(gbase) + (voff)[_i]), (PG8_LAS unsigned*)(lds + (bufoff) + ldsw + _i * 8192), 16, 0, 0); } while (0)
; #define PG8_LDA(dst, b, h) do { _Pragma("unroll") for (int m = 0; m < 4; ++m) _Pragma("unroll") for (int k = 0; k < 2; ++k) dst[m][k] = *(const PG8_LAS bf16x8*)(lds + PG8_SA(b, h) + aoff + m * 2048 + k * 1024); } while (0)
; #define PG8_LDB(dst, b, h) do { _Pragma("unroll") for (int n = 0; n < 2; ++n) _Pragma("unroll") for (int k = 0; k < 2; ++k) dst[n][k] = *(const PG8_LAS bf16x8*)(lds + PG8_SB(b, h) + boff + n * 2048 + k * 1024); } while (0)
; #define PG8_MMA(ai, bj, At, Bt) do { __builtin_amdgcn_s_setprio(1); _Pragma("unroll") for (int m = 0; m < 4; ++m) _Pragma("unroll") for (int n = 0; n < 2; ++n) _Pragma("unroll") for (int k = 0; k < 2; ++k) \
;         acc[ai][bj][m][n] = __builtin_amdgcn_mfma_f32_16x16x32_bf16(Bt[n][k], At[m][k], acc[ai][bj][m][n], 0, 0, 0); __builtin_amdgcn_s_setprio(0); } while (0)
; #define PG8_WAIT_V(n) asm volatile("s_waitcnt vmcnt(" #n ")" ::: "memory")
; #define PG8_WAIT_L(n) asm volatile("s_waitcnt lgkmcnt(" #n ")" ::: "memory")
; #define PG8_BAR __builtin_amdgcn_s_barrier()
; #define PG8_SCHED __builtin_amdgcn_sched_barrier(0)
; template <class Epi, class Sched, bool ALIGN_EPI = false, bool SP2 = false>
; __device__ __forceinline__ void gemm_phase(PG8_LAS unsigned char* lds, const Gemm g, const Sched& S, const Epi& E) {
;     ...
;             PG8_WAIT_V(8); PG8_WAIT_L(0); PG8_BAR; PG8_MMA(1, 0, At, B0); PG8_MMA(1, 1, At, B1); PG8_BAR; PG8_SCHED;
;             PG8_LDB(B0, 1, 0); PG8_LDB(B1, 1, 1); PG8_SCHED; PG8_LDA(At, 1, 0); PG8_STAGE(PG8_SA(0, 1), a2 + hstepA, voffA);
;             PG8_WAIT_V(8); PG8_WAIT_L(0); PG8_BAR; PG8_MMA(0, 0, At, B0); PG8_MMA(0, 1, At, B1); PG8_BAR; PG8_SCHED;
	v_mfma_f32_16x16x32_bf16 v[60:63], v[166:169], v[202:205], 0
	v_mfma_f32_16x16x32_bf16 v[56:59], v[174:177], v[202:205], 0
	v_mfma_f32_16x16x32_bf16 v[48:51], v[166:169], v[210:213], 0
	v_mfma_f32_16x16x32_bf16 v[40:43], v[174:177], v[210:213], 0
	v_mfma_f32_16x16x32_bf16 v[32:35], v[166:169], v[218:221], 0
	v_mfma_f32_16x16x32_bf16 v[24:27], v[174:177], v[218:221], 0
	v_mfma_f32_16x16x32_bf16 v[16:19], v[166:169], v[226:229], 0
	v_mfma_f32_16x16x32_bf16 v[8:11], v[174:177], v[226:229], 0
	v_mfma_f32_16x16x32_bf16 v[60:63], v[170:173], v[206:209], v[60:63]
	v_mfma_f32_16x16x32_bf16 v[56:59], v[178:181], v[206:209], v[56:59]
	v_mfma_f32_16x16x32_bf16 v[48:51], v[170:173], v[214:217], v[48:51]
	v_mfma_f32_16x16x32_bf16 v[40:43], v[178:181], v[214:217], v[40:43]
	v_mfma_f32_16x16x32_bf16 v[32:35], v[170:173], v[222:225], v[32:35]
	v_mfma_f32_16x16x32_bf16 v[24:27], v[178:181], v[222:225], v[24:27]
	v_mfma_f32_16x16x32_bf16 v[16:19], v[170:173], v[230:233], v[16:19]
	v_mfma_f32_16x16x32_bf16 v[8:11], v[178:181], v[230:233], v[8:11]
	s_setprio 0
	s_setprio 1
	v_mfma_f32_16x16x32_bf16 v[52:55], v[186:189], v[202:205], 0
	v_mfma_f32_16x16x32_bf16 v[44:47], v[194:197], v[202:205], 0
	v_mfma_f32_16x16x32_bf16 v[36:39], v[186:189], v[210:213], 0
	v_mfma_f32_16x16x32_bf16 v[28:31], v[194:197], v[210:213], 0
	v_mfma_f32_16x16x32_bf16 v[20:23], v[186:189], v[218:221], 0
	v_mfma_f32_16x16x32_bf16 v[12:15], v[194:197], v[218:221], 0
	v_mfma_f32_16x16x32_bf16 v[4:7], v[186:189], v[226:229], 0
	v_mfma_f32_16x16x32_bf16 v[0:3], v[194:197], v[226:229], 0
	v_mfma_f32_16x16x32_bf16 v[52:55], v[190:193], v[206:209], v[52:55]
	v_mfma_f32_16x16x32_bf16 v[44:47], v[198:201], v[206:209], v[44:47]
	v_mfma_f32_16x16x32_bf16 v[36:39], v[190:193], v[214:217], v[36:39]
	v_mfma_f32_16x16x32_bf16 v[28:31], v[198:201], v[214:217], v[28:31]
	v_mfma_f32_16x16x32_bf16 v[20:23], v[190:193], v[222:225], v[20:23]
	v_mfma_f32_16x16x32_bf16 v[12:15], v[198:201], v[222:225], v[12:15]
	v_mfma_f32_16x16x32_bf16 v[4:7], v[190:193], v[230:233], v[4:7]
	v_mfma_f32_16x16x32_bf16 v[0:3], v[198:201], v[230:233], v[0:3]
	s_barrier
	s_setprio 0
	s_add_i32 s47, 0, 0x18000
	s_add_i32 s55, 0, 0x1c000
	v_add_u32_e32 v178, s47, v160
	v_add_u32_e32 v185, s55, v160
	ds_read_b128 v[166:169], v178
	ds_read_b128 v[170:173], v178 offset:1024
	ds_read_b128 v[174:177], v178 offset:2048
	ds_read_b128 v[178:181], v178 offset:3072
	ds_read_b128 v[186:189], v185
	ds_read_b128 v[190:193], v185 offset:1024
	ds_read_b128 v[194:197], v185 offset:2048
	ds_read_b128 v[198:201], v185 offset:3072
	s_add_u32 s58, s58, 0x80000
	s_addc_u32 s59, s59, 0
	s_mov_b32 m0, s11
	v_lshl_add_u64 v[238:239], s[58:59], 0, v[128:129]
	ds_read_b128 v[202:205], v165 offset:32768
	ds_read_b128 v[206:209], v165 offset:33792
	ds_read_b128 v[210:213], v165 offset:34816
	ds_read_b128 v[214:217], v165 offset:35840
	ds_read_b128 v[218:221], v165 offset:36864
	ds_read_b128 v[222:225], v165 offset:37888
	ds_read_b128 v[226:229], v165 offset:38912
	ds_read_b128 v[230:233], v165 offset:39936
	global_load_lds_dwordx4 v[238:239], off
	v_lshl_add_u64 v[238:239], s[58:59], 0, v[132:133]
	s_mov_b32 m0, s12
	s_nop 0
	global_load_lds_dwordx4 v[238:239], off
	s_waitcnt vmcnt(8)
	s_waitcnt lgkmcnt(0)
	s_setprio 1
	s_barrier
	v_mfma_f32_16x16x32_bf16 v[124:127], v[166:169], v[202:205], v[124:127]
	v_mfma_f32_16x16x32_bf16 v[120:123], v[174:177], v[202:205], v[120:123]
	v_mfma_f32_16x16x32_bf16 v[112:115], v[166:169], v[210:213], v[112:115]
	v_mfma_f32_16x16x32_bf16 v[104:107], v[174:177], v[210:213], v[104:107]
	v_mfma_f32_16x16x32_bf16 v[96:99], v[166:169], v[218:221], v[96:99]
	v_mfma_f32_16x16x32_bf16 v[88:91], v[174:177], v[218:221], v[88:91]
	v_mfma_f32_16x16x32_bf16 v[80:83], v[166:169], v[226:229], v[80:83]
	v_mfma_f32_16x16x32_bf16 v[72:75], v[174:177], v[226:229], v[72:75]
	v_mfma_f32_16x16x32_bf16 v[124:127], v[170:173], v[206:209], v[124:127]
	v_mfma_f32_16x16x32_bf16 v[120:123], v[178:181], v[206:209], v[120:123]
	v_mfma_f32_16x16x32_bf16 v[112:115], v[170:173], v[214:217], v[112:115]
	v_mfma_f32_16x16x32_bf16 v[104:107], v[178:181], v[214:217], v[104:107]
	v_mfma_f32_16x16x32_bf16 v[96:99], v[170:173], v[222:225], v[96:99]
	v_mfma_f32_16x16x32_bf16 v[88:91], v[178:181], v[222:225], v[88:91]
	v_mfma_f32_16x16x32_bf16 v[80:83], v[170:173], v[230:233], v[80:83]
	v_mfma_f32_16x16x32_bf16 v[72:75], v[178:181], v[230:233], v[72:75]
	s_setprio 0
	s_setprio 1
	v_mfma_f32_16x16x32_bf16 v[116:119], v[186:189], v[202:205], v[116:119]
	v_mfma_f32_16x16x32_bf16 v[108:111], v[194:197], v[202:205], v[108:111]
	v_mfma_f32_16x16x32_bf16 v[100:103], v[186:189], v[210:213], v[100:103]
	v_mfma_f32_16x16x32_bf16 v[92:95], v[194:197], v[210:213], v[92:95]
	v_mfma_f32_16x16x32_bf16 v[84:87], v[186:189], v[218:221], v[84:87]
	v_mfma_f32_16x16x32_bf16 v[76:79], v[194:197], v[218:221], v[76:79]
	v_mfma_f32_16x16x32_bf16 v[68:71], v[186:189], v[226:229], v[68:71]
	v_mfma_f32_16x16x32_bf16 v[64:67], v[194:197], v[226:229], v[64:67]
	v_mfma_f32_16x16x32_bf16 v[116:119], v[190:193], v[206:209], v[116:119]
	v_mfma_f32_16x16x32_bf16 v[108:111], v[198:201], v[206:209], v[108:111]
	v_mfma_f32_16x16x32_bf16 v[100:103], v[190:193], v[214:217], v[100:103]
	v_mfma_f32_16x16x32_bf16 v[92:95], v[198:201], v[214:217], v[92:95]
	v_mfma_f32_16x16x32_bf16 v[84:87], v[190:193], v[222:225], v[84:87]
	v_mfma_f32_16x16x32_bf16 v[76:79], v[198:201], v[222:225], v[76:79]
	v_mfma_f32_16x16x32_bf16 v[68:71], v[190:193], v[230:233], v[68:71]
	v_mfma_f32_16x16x32_bf16 v[64:67], v[198:201], v[230:233], v[64:67]
	s_barrier
; #define PG8_STAGE(bufoff, gbase, voff) do { _Pragma("unroll") for (int _i = 0; _i < 2; ++_i) \
;         __builtin_amdgcn_global_load_lds((const unsigned*)((const char*)(gbase) + (voff)[_i]), (PG8_LAS unsigned*)(lds + (bufoff) + ldsw + _i * 8192), 16, 0, 0); } while (0)
; #define PG8_LDA(dst, b, h) do { _Pragma("unroll") for (int m = 0; m < 4; ++m) _Pragma("unroll") for (int k = 0; k < 2; ++k) dst[m][k] = *(const PG8_LAS bf16x8*)(lds + PG8_SA(b, h) + aoff + m * 2048 + k * 1024); } while (0)
; #define PG8_MMA(ai, bj, At, Bt) do { __builtin_amdgcn_s_setprio(1); _Pragma("unroll") for (int m = 0; m < 4; ++m) _Pragma("unroll") for (int n = 0; n < 2; ++n) _Pragma("unroll") for (int k = 0; k < 2; ++k) \
;         acc[ai][bj][m][n] = __builtin_amdgcn_mfma_f32_16x16x32_bf16(Bt[n][k], At[m][k], acc[ai][bj][m][n], 0, 0, 0); __builtin_amdgcn_s_setprio(0); } while (0)
; #define PG8_WAIT_V(n) asm volatile("s_waitcnt vmcnt(" #n ")" ::: "memory")
; #define PG8_WAIT_L(n) asm volatile("s_waitcnt lgkmcnt(" #n ")" ::: "memory")
; #define PG8_BAR __builtin_amdgcn_s_barrier()
; #define PG8_SCHED __builtin_amdgcn_sched_barrier(0)
; template <class Epi, class Sched, bool ALIGN_EPI = false, bool SP2 = false>
; __device__ __forceinline__ void gemm_phase(PG8_LAS unsigned char* lds, const Gemm g, const Sched& S, const Epi& E) {
;     ...
;             PG8_LDA(At, 1, 1); PG8_STAGE(PG8_SB(1, 0), b3, voffB); PG8_STAGE(PG8_SB(1, 1), b3 + hstepB, voffB); PG8_STAGE(PG8_SA(1, 0), a3, voffA);
;             PG8_WAIT_V(8); PG8_WAIT_L(0); PG8_BAR; PG8_MMA(1, 0, At, B0); PG8_MMA(1, 1, At, B1); PG8_BAR; PG8_SCHED;
	s_setprio 0
	s_add_i32 s47, s47, s8
	v_lshl_add_u64 v[158:159], v[158:159], 0, s[38:39]
	s_mov_b32 m0, s47
	ds_read_b128 v[202:205], v165 offset:49152
	ds_read_b128 v[206:209], v165 offset:50176
	ds_read_b128 v[210:213], v165 offset:51200
	ds_read_b128 v[214:217], v165 offset:52224
	ds_read_b128 v[218:221], v165 offset:53248
	ds_read_b128 v[222:225], v165 offset:54272
	ds_read_b128 v[226:229], v165 offset:55296
	ds_read_b128 v[230:233], v165 offset:56320
	global_load_lds_dwordx4 v[158:159], off
	s_add_i32 m0, s47, 0x2000
	s_add_u32 s52, s52, 0x80080
	v_lshl_add_u64 v[158:159], v[182:183], 0, s[38:39]
	s_addc_u32 s53, s53, 0
	s_add_i32 s47, s55, s8
	global_load_lds_dwordx4 v[158:159], off
	v_lshl_add_u64 v[158:159], s[52:53], 0, v[130:131]
	s_mov_b32 m0, s47
	s_nop 0
	global_load_lds_dwordx4 v[158:159], off
	v_lshl_add_u64 v[158:159], s[52:53], 0, v[134:135]
	s_add_i32 m0, s47, 0x2000
	s_nop 0
	global_load_lds_dwordx4 v[158:159], off
	v_lshl_add_u64 v[158:159], v[234:235], 0, s[38:39]
	s_mov_b32 m0, s13
	s_nop 0
	global_load_lds_dwordx4 v[158:159], off
	v_lshl_add_u64 v[158:159], v[236:237], 0, s[38:39]
	s_mov_b32 m0, s33
	s_nop 0
	global_load_lds_dwordx4 v[158:159], off
	s_waitcnt vmcnt(8)
	s_waitcnt lgkmcnt(0)
	s_setprio 1
	s_barrier
	v_mfma_f32_16x16x32_bf16 v[60:63], v[166:169], v[202:205], v[60:63]
	v_mfma_f32_16x16x32_bf16 v[56:59], v[174:177], v[202:205], v[56:59]
	v_mfma_f32_16x16x32_bf16 v[48:51], v[166:169], v[210:213], v[48:51]
	v_mfma_f32_16x16x32_bf16 v[40:43], v[174:177], v[210:213], v[40:43]
	v_mfma_f32_16x16x32_bf16 v[32:35], v[166:169], v[218:221], v[32:35]
	v_mfma_f32_16x16x32_bf16 v[24:27], v[174:177], v[218:221], v[24:27]
	v_mfma_f32_16x16x32_bf16 v[16:19], v[166:169], v[226:229], v[16:19]
	v_mfma_f32_16x16x32_bf16 v[8:11], v[174:177], v[226:229], v[8:11]
	v_mfma_f32_16x16x32_bf16 v[60:63], v[170:173], v[206:209], v[60:63]
	v_mfma_f32_16x16x32_bf16 v[56:59], v[178:181], v[206:209], v[56:59]
	v_mfma_f32_16x16x32_bf16 v[48:51], v[170:173], v[214:217], v[48:51]
	v_mfma_f32_16x16x32_bf16 v[40:43], v[178:181], v[214:217], v[40:43]
	v_mfma_f32_16x16x32_bf16 v[32:35], v[170:173], v[222:225], v[32:35]
	v_mfma_f32_16x16x32_bf16 v[24:27], v[178:181], v[222:225], v[24:27]
	v_mfma_f32_16x16x32_bf16 v[16:19], v[170:173], v[230:233], v[16:19]
	v_mfma_f32_16x16x32_bf16 v[8:11], v[178:181], v[230:233], v[8:11]
	s_setprio 0
	s_setprio 1
	v_mfma_f32_16x16x32_bf16 v[52:55], v[186:189], v[202:205], v[52:55]
	v_mfma_f32_16x16x32_bf16 v[44:47], v[194:197], v[202:205], v[44:47]
	v_mfma_f32_16x16x32_bf16 v[36:39], v[186:189], v[210:213], v[36:39]
	v_mfma_f32_16x16x32_bf16 v[28:31], v[194:197], v[210:213], v[28:31]
	v_mfma_f32_16x16x32_bf16 v[20:23], v[186:189], v[218:221], v[20:23]
	v_mfma_f32_16x16x32_bf16 v[12:15], v[194:197], v[218:221], v[12:15]
	v_mfma_f32_16x16x32_bf16 v[4:7], v[186:189], v[226:229], v[4:7]
	v_mfma_f32_16x16x32_bf16 v[0:3], v[194:197], v[226:229], v[0:3]
	v_mfma_f32_16x16x32_bf16 v[52:55], v[190:193], v[206:209], v[52:55]
	v_mfma_f32_16x16x32_bf16 v[44:47], v[198:201], v[206:209], v[44:47]
	v_mfma_f32_16x16x32_bf16 v[36:39], v[190:193], v[214:217], v[36:39]
	v_mfma_f32_16x16x32_bf16 v[28:31], v[198:201], v[214:217], v[28:31]
	v_mfma_f32_16x16x32_bf16 v[20:23], v[190:193], v[222:225], v[20:23]
	v_mfma_f32_16x16x32_bf16 v[12:15], v[198:201], v[222:225], v[12:15]
	v_mfma_f32_16x16x32_bf16 v[4:7], v[190:193], v[230:233], v[4:7]
	v_mfma_f32_16x16x32_bf16 v[0:3], v[198:201], v[230:233], v[0:3]
	s_barrier
	s_setprio 0
	s_add_i32 s46, s46, 2
	s_add_u32 s50, s50, 0x100
	s_addc_u32 s51, s51, 0
	s_add_u32 s4, s4, 0x100
	s_addc_u32 s5, s5, 0
	s_cmp_gt_u32 s46, 29
	s_cbranch_scc1 .Lmy_peel_2_exit
	.p2alignl 6, 3212836864

; #define SLOAD(i, k0) do { sr_[i].vs0 = St::ld8(&Vh[(long)((k0) + sr) * LDK + sc]); sr_[i].vs1 = St::ld8(&Vh[(long)((k0) + 32 + sr) * LDK + sc]); \
;     sr_[i].ks0 = St::ld8(&Kh[(long)((k0) + sr) * LDK + sc]); sr_[i].ks1 = St::ld8(&Kh[(long)((k0) + 32 + sr) * LDK + sc]); } while (0)
; #define SWRITE(bo, i) do { *(bf16x8*)((char*)V_lds + (bo) + vst0) = St::tobf(sr_[i].vs0);            \
;     *(bf16x8*)((char*)V_lds + (bo) + vst1) = St::tobf(sr_[i].vs1); int kc = sc * 2;               \
;     *(bf16x8*)((char*)K_lds + (bo) + KSWZ(sr, kc)) = St::tobf(sr_[i].ks0);                       \
;     *(bf16x8*)((char*)K_lds + (bo) + KSWZ(32 + sr, kc)) = St::tobf(sr_[i].ks1); } while (0)
; #define SWAIT() do { if constexpr (SDEPTH == 2) asm volatile("s_waitcnt vmcnt(4)" ::: "memory"); else asm volatile("s_waitcnt vmcnt(0)" ::: "memory"); } while (0)
; __device__ __forceinline__ void partialSM(f32x16& p0, f32x16& p1, float& m_reg, float& mn, float& alpha, bool bounded) {
;     ...
;   for (int r = 0; r < 16; ++r) p0[r] = __builtin_amdgcn_exp2f(p0[r]);
; template <typename TQ> ...
;     ...
;   qkt(pA0, pA1, K_lds, qr, r32, hi); partialSM(pA0, pA1, m_reg, mnA, alA, bounded);
;   SLOAD(SO, KVBLK); if constexpr (SDEPTH == 2) { if (2 < NT) SLOAD(SE, 2 * KVBLK); }
;   SWAIT(); SWRITE((int)SHM_K, SO); __syncthreads();
;   int o_prev = 0, o_cur = (int)SHM_K, o_nxt = 2 * (int)SHM_K;
.LBB0_893:
	v_lshl_or_b32 v28, v26, 1, v16
	v_mov_b32_e32 v29, v17
	s_mov_b64 s[10:11], 0x4000
	v_lshl_add_u64 v[32:33], v[28:29], 0, s[10:11]
	s_mov_b64 s[10:11], 0x6000
	v_lshl_add_u64 v[34:35], v[28:29], 0, s[10:11]
	v_lshl_add_u64 v[18:19], s[38:39], 0, v[32:33]
	v_lshl_add_u64 v[22:23], s[38:39], 0, v[34:35]
	v_lshl_add_u64 v[32:33], s[34:35], 0, v[32:33]
	v_lshl_add_u64 v[36:37], s[34:35], 0, v[34:35]
	global_load_dwordx4 v[18:21], v[18:19], off
	s_nop 0
	global_load_dwordx4 v[22:25], v[22:23], off
	s_nop 0
	global_load_dwordx4 v[32:35], v[32:33], off
	s_nop 0
	global_load_dwordx4 v[36:39], v[36:37], off
	v_lshl_add_u64 v[40:41], v[28:29], 0, s[74:75]
	s_mov_b64 s[10:11], 0xa000
	v_lshl_add_u64 v[42:43], s[38:39], 0, v[40:41]
	v_lshl_add_u64 v[28:29], v[28:29], 0, s[10:11]
	v_lshl_add_u64 v[40:41], s[34:35], 0, v[40:41]
	v_lshl_add_u64 v[44:45], s[38:39], 0, v[28:29]
	global_load_dwordx4 v[144:147], v[42:43], off
	global_load_dwordx4 v[152:155], v[44:45], off
	v_lshl_add_u64 v[28:29], s[34:35], 0, v[28:29]
	global_load_dwordx4 v[148:151], v[40:41], off
	global_load_dwordx4 v[156:159], v[28:29], off
	s_add_i32 s10, 0, 0x18000
	v_lshlrev_b32_e32 v29, 4, v199
	v_lshlrev_b32_e32 v28, 3, v199
	v_lshlrev_b32_e32 v31, 1, v199
	v_exp_f32_e32 v161, v12
	v_exp_f32_e32 v163, v13
	v_exp_f32_e32 v160, v14
	v_exp_f32_e32 v162, v15
	v_mad_i64_i32 v[12:13], s[4:5], s4, v195, v[16:17]
	v_and_b32_e32 v14, 15, v179
	v_and_b32_e32 v15, 0xc0, v29
	s_cmp_lg_u32 0, -1
	v_exp_f32_e32 v173, v0
	v_exp_f32_e32 v175, v1
	v_exp_f32_e32 v171, v2
	v_exp_f32_e32 v174, v3
	v_exp_f32_e32 v170, v4
	v_exp_f32_e32 v172, v5
	v_exp_f32_e32 v168, v6
	v_exp_f32_e32 v169, v7
	v_exp_f32_e32 v165, v8
	v_exp_f32_e32 v167, v9
	v_exp_f32_e32 v164, v10
	v_exp_f32_e32 v166, v11
	v_and_b32_e32 v16, 32, v31
	v_and_b32_e32 v17, 0x100, v28
	v_lshl_or_b32 v12, v14, 4, v12
	v_and_or_b32 v14, v28, 24, v15
	s_cselect_b32 s4, 0, 0
	s_add_i32 s5, 0, 0x10000
	v_and_b32_e32 v26, 0x3fffffc0, v179
	v_lshl_add_u64 v[182:183], s[72:73], 0, v[12:13]
	v_or3_b32 v216, v14, v16, v17
	s_waitcnt vmcnt(4)
	v_add_u32_e32 v12, s5, v208
	v_add_u32_e32 v13, s5, v210
	v_mov_b32_e32 v14, v177
	v_mov_b32_e32 v15, v177
	v_mov_b32_e32 v0, v177
	v_mov_b32_e32 v1, v177
	v_mov_b32_e32 v2, v177
	v_mov_b32_e32 v3, v177
	v_mov_b32_e32 v4, v177
	v_mov_b32_e32 v5, v177
	v_mov_b32_e32 v6, v177
	v_mov_b32_e32 v7, v177
	v_mov_b32_e32 v8, v177
	v_mov_b32_e32 v9, v177
	v_mov_b32_e32 v10, v177
	v_mov_b32_e32 v11, v177
	v_lshl_add_u32 v179, v26, 2, s10
	s_mov_b32 s3, 1
	s_mov_b32 s9, 0
	v_cmp_gt_u32_e64 s[40:41], 32, v199
	v_lshl_add_u32 v181, v197, 2, v179
	v_add_u32_e32 v217, s4, v216
	v_mov_b32_e32 v200, 0
	s_movk_i32 s10, 0x4000
	s_mov_b32 s4, 0x8000
	s_waitcnt vmcnt(7)
	ds_write_b128 v27, v[18:21] offset:16384
	s_waitcnt vmcnt(6)
	ds_write_b128 v30, v[22:25] offset:16384
	s_waitcnt vmcnt(5)
	ds_write_b128 v12, v[32:35]
	s_waitcnt vmcnt(4)
	ds_write_b128 v13, v[36:39]
	v_mov_b32_e32 v12, v177
	v_mov_b32_e32 v13, v177
	v_mov_b64_e32 v[62:63], v[14:15]
	v_mov_b64_e32 v[46:47], v[14:15]
	v_mov_b64_e32 v[30:31], v[14:15]
	v_mov_b64_e32 v[60:61], v[12:13]
	v_mov_b64_e32 v[58:59], v[10:11]
	v_mov_b64_e32 v[56:57], v[8:9]
	v_mov_b64_e32 v[54:55], v[6:7]
	v_mov_b64_e32 v[52:53], v[4:5]
	v_mov_b64_e32 v[50:51], v[2:3]
	v_mov_b64_e32 v[48:49], v[0:1]
	v_mov_b64_e32 v[44:45], v[12:13]
	v_mov_b64_e32 v[42:43], v[10:11]
	v_mov_b64_e32 v[40:41], v[8:9]
	v_mov_b64_e32 v[38:39], v[6:7]
	v_mov_b64_e32 v[36:37], v[4:5]
	v_mov_b64_e32 v[34:35], v[2:3]
	v_mov_b64_e32 v[32:33], v[0:1]
	v_mov_b64_e32 v[28:29], v[12:13]
	v_mov_b64_e32 v[26:27], v[10:11]
	v_mov_b64_e32 v[24:25], v[8:9]
	v_mov_b64_e32 v[22:23], v[6:7]
	v_mov_b64_e32 v[20:21], v[4:5]
	v_mov_b64_e32 v[18:19], v[2:3]
	v_mov_b64_e32 v[16:17], v[0:1]
	s_waitcnt lgkmcnt(0)
	s_barrier
	.p2alignl 6, 3212836864

;     __device__ __forceinline__ void a_ready(const Unit& u) const {
;     ...
;         }
;         asm volatile("" ::: "memory"); __builtin_amdgcn_s_barrier(); asm volatile("" ::: "memory");
.LBB0_1047:
	s_or_b64 exec, exec, s[46:47]
	s_barrier
	.p2alignl 6, 3212836864

; #define PG8_STAGE(bufoff, gbase, voff) do { _Pragma("unroll") for (int _i = 0; _i < 2; ++_i) \
;         __builtin_amdgcn_global_load_lds((const unsigned*)((const char*)(gbase) + (voff)[_i]), (PG8_LAS unsigned*)(lds + (bufoff) + ldsw + _i * 8192), 16, 0, 0); } while (0)
; #define PG8_LDA(dst, b, h) do { _Pragma("unroll") for (int m = 0; m < 4; ++m) _Pragma("unroll") for (int k = 0; k < 2; ++k) dst[m][k] = *(const PG8_LAS bf16x8*)(lds + PG8_SA(b, h) + aoff + m * 2048 + k * 1024); } while (0)
; #define PG8_LDB(dst, b, h) do { _Pragma("unroll") for (int n = 0; n < 2; ++n) _Pragma("unroll") for (int k = 0; k < 2; ++k) dst[n][k] = *(const PG8_LAS bf16x8*)(lds + PG8_SB(b, h) + boff + n * 2048 + k * 1024); } while (0)
; #define PG8_WAIT_V(n) asm volatile("s_waitcnt vmcnt(" #n ")" ::: "memory")
; #define PG8_WAIT_L(n) asm volatile("s_waitcnt lgkmcnt(" #n ")" ::: "memory")
; template <class Epi, class Sched, bool ALIGN_EPI = false, bool SP2 = false>
; __device__ __forceinline__ void gemm_phase(PG8_LAS unsigned char* lds, const Gemm g, const Sched& S, const Epi& E) {
;     ...
;         const bool has_next = S.next(ui + 1, nxt);
;         const char* nA = has_next ? (const char*)g.A + (size_t)nxt.pm * tstepA + (size_t)nxt.z * g.azs + (size_t)(nxt.k0 >> 6) * kstA : cA; const char* nB = has_next ? (const char*)g.Bt + (size_t)nxt.pn * tstepB + (size_t)nxt.z * g.bzs + (size_t)nxt.k0 * 2 : cB;
;         const int nt = cur.nt;
;         for (int t = 0; t < nt; t += 2) {
;             const bool last = (t == nt - 2);
;             const char* a1 = cA + (size_t)(t + 1) * kstA;
;             const char* a2 = last ? nA : cA + (size_t)(t + 2) * kstA; const char* b2 = last ? nB : cB + (size_t)(t + 2) * kstep;
;             const char* a3 = a2 + kstA; const char* b3 = b2 + kstep;
;             if (last && has_next) S.a_ready(nxt);
;             if constexpr (SP2) {
;             PG8_LDB(B0, 0, 0); PG8_LDB(B1, 0, 1); PG8_SCHED; PG8_LDA(At, 0, 0); PG8_STAGE(PG8_SA(1, 1), a1 + hstepA, voffA);
;             PG8_WAIT_V(8); PG8_WAIT_L(0); PG8_BAR; PG8_MMA(0, 0, At, B0); PG8_MMA(0, 1, At, B1); PG8_BAR; PG8_SCHED;
;             PG8_LDA(At, 0, 1); PG8_STAGE(PG8_SB(0, 0), b2, voffB); PG8_STAGE(PG8_SB(0, 1), b2 + hstepB, voffB); PG8_STAGE(PG8_SA(0, 0), a2, voffA);
;             PG8_WAIT_V(8); PG8_WAIT_L(0); PG8_BAR; PG8_MMA(1, 0, At, B0); PG8_MMA(1, 1, At, B1); PG8_BAR; PG8_SCHED;
.LBB0_1306:
	s_ashr_i32 s41, s40, 31
	s_lshl_b64 s[4:5], s[40:41], 20
	v_readlane_b32 s12, v254, 41
	v_readlane_b32 s13, v254, 42
	s_add_u32 s44, s12, s4
	s_addc_u32 s45, s13, s5
	s_and_b64 s[4:5], s[42:43], exec
	s_cselect_b32 s4, s45, s51
	s_cselect_b32 s5, s44, s50
	s_ashr_i32 s39, s38, 31
	s_lshl_b64 s[12:13], s[38:39], 20
	s_add_u32 s48, s3, s12
	s_addc_u32 s49, s10, s13
	s_and_b64 s[12:13], s[42:43], exec
	s_cselect_b32 s12, s49, s53
	s_cselect_b32 s13, s48, s52
	s_add_u32 s50, s50, 0x80080
	s_addc_u32 s51, s51, 0
	s_add_u32 s39, s52, 0x100
	s_addc_u32 s41, s53, 0
	s_mov_b32 s63, -2
	ds_read_b128 v[156:159], v152
	ds_read_b128 v[160:163], v152 offset:1024
	ds_read_b128 v[164:167], v152 offset:2048
	ds_read_b128 v[168:171], v152 offset:3072
	ds_read_b128 v[172:175], v153
	ds_read_b128 v[176:179], v153 offset:1024
	ds_read_b128 v[180:183], v153 offset:2048
	ds_read_b128 v[190:193], v153 offset:3072
	s_add_u32 s52, s50, 0xfff80080
	s_addc_u32 s53, s51, -1
	s_cmp_eq_u32 s63, 28
	s_cselect_b32 s59, s4, s53
	s_cselect_b32 s58, s5, s52
	s_cselect_b32 s53, s12, s41
	s_cselect_b32 s52, s13, s39
	v_lshl_add_u64 v[226:227], s[50:51], 0, v[142:143]
	s_add_i32 m0, s7, 0xc000
	ds_read_b128 v[194:197], v154
	ds_read_b128 v[198:201], v154 offset:1024
	ds_read_b128 v[202:205], v154 offset:2048
	ds_read_b128 v[206:209], v154 offset:3072
	ds_read_b128 v[210:213], v154 offset:4096
	ds_read_b128 v[214:217], v154 offset:5120
	ds_read_b128 v[218:221], v154 offset:6144
	ds_read_b128 v[222:225], v154 offset:7168
	global_load_lds_dwordx4 v[226:227], off
	v_lshl_add_u64 v[226:227], s[50:51], 0, v[144:145]
	s_add_i32 m0, s7, 0xe000
	s_nop 0
	global_load_lds_dwordx4 v[226:227], off
	s_waitcnt vmcnt(8)
	s_waitcnt lgkmcnt(0)
	s_setprio 1
	s_barrier
	v_mfma_f32_16x16x32_bf16 v[124:127], v[156:159], v[194:197], 0
	v_mfma_f32_16x16x32_bf16 v[120:123], v[164:167], v[194:197], 0
	v_mfma_f32_16x16x32_bf16 v[108:111], v[156:159], v[202:205], 0
	v_mfma_f32_16x16x32_bf16 v[104:107], v[164:167], v[202:205], 0
	v_mfma_f32_16x16x32_bf16 v[92:95], v[156:159], v[210:213], 0
	v_mfma_f32_16x16x32_bf16 v[88:91], v[164:167], v[210:213], 0
	v_mfma_f32_16x16x32_bf16 v[76:79], v[156:159], v[218:221], 0
	v_mfma_f32_16x16x32_bf16 v[72:75], v[164:167], v[218:221], 0
	v_mfma_f32_16x16x32_bf16 v[124:127], v[160:163], v[198:201], v[124:127]
	v_mfma_f32_16x16x32_bf16 v[120:123], v[168:171], v[198:201], v[120:123]
	v_mfma_f32_16x16x32_bf16 v[108:111], v[160:163], v[206:209], v[108:111]
	v_mfma_f32_16x16x32_bf16 v[104:107], v[168:171], v[206:209], v[104:107]
	v_mfma_f32_16x16x32_bf16 v[92:95], v[160:163], v[214:217], v[92:95]
	v_mfma_f32_16x16x32_bf16 v[88:91], v[168:171], v[214:217], v[88:91]
	v_mfma_f32_16x16x32_bf16 v[76:79], v[160:163], v[222:225], v[76:79]
	v_mfma_f32_16x16x32_bf16 v[72:75], v[168:171], v[222:225], v[72:75]
	s_setprio 0
	s_setprio 1
	v_mfma_f32_16x16x32_bf16 v[116:119], v[172:175], v[194:197], 0
	v_mfma_f32_16x16x32_bf16 v[112:115], v[180:183], v[194:197], 0
	v_mfma_f32_16x16x32_bf16 v[100:103], v[172:175], v[202:205], 0
	v_mfma_f32_16x16x32_bf16 v[96:99], v[180:183], v[202:205], 0
	v_mfma_f32_16x16x32_bf16 v[84:87], v[172:175], v[210:213], 0
	v_mfma_f32_16x16x32_bf16 v[80:83], v[180:183], v[210:213], 0
	v_mfma_f32_16x16x32_bf16 v[68:71], v[172:175], v[218:221], 0
	v_mfma_f32_16x16x32_bf16 v[64:67], v[180:183], v[218:221], 0
	v_mfma_f32_16x16x32_bf16 v[116:119], v[176:179], v[198:201], v[116:119]
	v_mfma_f32_16x16x32_bf16 v[112:115], v[190:193], v[198:201], v[112:115]
	v_mfma_f32_16x16x32_bf16 v[100:103], v[176:179], v[206:209], v[100:103]
	v_mfma_f32_16x16x32_bf16 v[96:99], v[190:193], v[206:209], v[96:99]
	v_mfma_f32_16x16x32_bf16 v[84:87], v[176:179], v[214:217], v[84:87]
	v_mfma_f32_16x16x32_bf16 v[80:83], v[190:193], v[214:217], v[80:83]
	v_mfma_f32_16x16x32_bf16 v[68:71], v[176:179], v[222:225], v[68:71]
	v_mfma_f32_16x16x32_bf16 v[64:67], v[190:193], v[222:225], v[64:67]
	s_barrier
	s_setprio 0
	s_add_i32 s64, s57, s6
	v_lshl_add_u64 v[226:227], s[52:53], 0, v[130:131]
	s_mov_b32 m0, s64
	ds_read_b128 v[194:197], v154 offset:16384
	ds_read_b128 v[198:201], v154 offset:17408
	ds_read_b128 v[202:205], v154 offset:18432
	ds_read_b128 v[206:209], v154 offset:19456
	ds_read_b128 v[210:213], v154 offset:20480
	ds_read_b128 v[214:217], v154 offset:21504
	ds_read_b128 v[218:221], v154 offset:22528
	ds_read_b128 v[222:225], v154 offset:23552
	global_load_lds_dwordx4 v[226:227], off
	s_add_i32 m0, s64, 0x2000
	s_add_u32 s64, s52, 0x80000
	v_lshl_add_u64 v[228:229], s[52:53], 0, v[134:135]
	s_addc_u32 s65, s53, 0
	s_add_i32 s66, s61, s6
	global_load_lds_dwordx4 v[228:229], off
	v_lshl_add_u64 v[230:231], s[64:65], 0, v[130:131]
	s_mov_b32 m0, s66
	v_lshl_add_u64 v[232:233], s[58:59], 0, v[132:133]
	global_load_lds_dwordx4 v[230:231], off
	v_lshl_add_u64 v[230:231], s[64:65], 0, v[134:135]
	s_add_i32 m0, s66, 0x2000
	s_nop 0
	global_load_lds_dwordx4 v[230:231], off
	v_lshl_add_u64 v[230:231], s[58:59], 0, v[128:129]
	s_mov_b32 m0, s7
	s_nop 0
	global_load_lds_dwordx4 v[230:231], off
	s_mov_b32 m0, s8
	s_nop 0
	global_load_lds_dwordx4 v[232:233], off
	s_waitcnt vmcnt(8)
	s_waitcnt lgkmcnt(0)
	s_setprio 1
	s_barrier
; #define PG8_STAGE(bufoff, gbase, voff) do { _Pragma("unroll") for (int _i = 0; _i < 2; ++_i) \
;         __builtin_amdgcn_global_load_lds((const unsigned*)((const char*)(gbase) + (voff)[_i]), (PG8_LAS unsigned*)(lds + (bufoff) + ldsw + _i * 8192), 16, 0, 0); } while (0)
; #define PG8_LDA(dst, b, h) do { _Pragma("unroll") for (int m = 0; m < 4; ++m) _Pragma("unroll") for (int k = 0; k < 2; ++k) dst[m][k] = *(const PG8_LAS bf16x8*)(lds + PG8_SA(b, h) + aoff + m * 2048 + k * 1024); } while (0)
; #define PG8_LDB(dst, b, h) do { _Pragma("unroll") for (int n = 0; n < 2; ++n) _Pragma("unroll") for (int k = 0; k < 2; ++k) dst[n][k] = *(const PG8_LAS bf16x8*)(lds + PG8_SB(b, h) + boff + n * 2048 + k * 1024); } while (0)
; #define PG8_MMA(ai, bj, At, Bt) do { __builtin_amdgcn_s_setprio(1); _Pragma("unroll") for (int m = 0; m < 4; ++m) _Pragma("unroll") for (int n = 0; n < 2; ++n) _Pragma("unroll") for (int k = 0; k < 2; ++k) \
;         acc[ai][bj][m][n] = __builtin_amdgcn_mfma_f32_16x16x32_bf16(Bt[n][k], At[m][k], acc[ai][bj][m][n], 0, 0, 0); __builtin_amdgcn_s_setprio(0); } while (0)
; #define PG8_WAIT_V(n) asm volatile("s_waitcnt vmcnt(" #n ")" ::: "memory")
; #define PG8_WAIT_L(n) asm volatile("s_waitcnt lgkmcnt(" #n ")" ::: "memory")
; #define PG8_BAR __builtin_amdgcn_s_barrier()
; #define PG8_SCHED __builtin_amdgcn_sched_barrier(0)
; template <class Epi, class Sched, bool ALIGN_EPI = false, bool SP2 = false>
; __device__ __forceinline__ void gemm_phase(PG8_LAS unsigned char* lds, const Gemm g, const Sched& S, const Epi& E) {
;     ...
;             PG8_WAIT_V(8); PG8_WAIT_L(0); PG8_BAR; PG8_MMA(1, 0, At, B0); PG8_MMA(1, 1, At, B1); PG8_BAR; PG8_SCHED;
;             PG8_LDB(B0, 1, 0); PG8_LDB(B1, 1, 1); PG8_SCHED; PG8_LDA(At, 1, 0); PG8_STAGE(PG8_SA(0, 1), a2 + hstepA, voffA);
;             PG8_WAIT_V(8); PG8_WAIT_L(0); PG8_BAR; PG8_MMA(0, 0, At, B0); PG8_MMA(0, 1, At, B1); PG8_BAR; PG8_SCHED;
	v_mfma_f32_16x16x32_bf16 v[60:63], v[156:159], v[194:197], 0
	v_mfma_f32_16x16x32_bf16 v[56:59], v[164:167], v[194:197], 0
	v_mfma_f32_16x16x32_bf16 v[44:47], v[156:159], v[202:205], 0
	v_mfma_f32_16x16x32_bf16 v[40:43], v[164:167], v[202:205], 0
	v_mfma_f32_16x16x32_bf16 v[28:31], v[156:159], v[210:213], 0
	v_mfma_f32_16x16x32_bf16 v[24:27], v[164:167], v[210:213], 0
	v_mfma_f32_16x16x32_bf16 v[12:15], v[156:159], v[218:221], 0
	v_mfma_f32_16x16x32_bf16 v[8:11], v[164:167], v[218:221], 0
	v_mfma_f32_16x16x32_bf16 v[60:63], v[160:163], v[198:201], v[60:63]
	v_mfma_f32_16x16x32_bf16 v[56:59], v[168:171], v[198:201], v[56:59]
	v_mfma_f32_16x16x32_bf16 v[44:47], v[160:163], v[206:209], v[44:47]
	v_mfma_f32_16x16x32_bf16 v[40:43], v[168:171], v[206:209], v[40:43]
	v_mfma_f32_16x16x32_bf16 v[28:31], v[160:163], v[214:217], v[28:31]
	v_mfma_f32_16x16x32_bf16 v[24:27], v[168:171], v[214:217], v[24:27]
	v_mfma_f32_16x16x32_bf16 v[12:15], v[160:163], v[222:225], v[12:15]
	v_mfma_f32_16x16x32_bf16 v[8:11], v[168:171], v[222:225], v[8:11]
	s_setprio 0
	s_setprio 1
	v_mfma_f32_16x16x32_bf16 v[52:55], v[172:175], v[194:197], 0
	v_mfma_f32_16x16x32_bf16 v[48:51], v[180:183], v[194:197], 0
	v_mfma_f32_16x16x32_bf16 v[36:39], v[172:175], v[202:205], 0
	v_mfma_f32_16x16x32_bf16 v[32:35], v[180:183], v[202:205], 0
	v_mfma_f32_16x16x32_bf16 v[20:23], v[172:175], v[210:213], 0
	v_mfma_f32_16x16x32_bf16 v[16:19], v[180:183], v[210:213], 0
	v_mfma_f32_16x16x32_bf16 v[4:7], v[172:175], v[218:221], 0
	v_mfma_f32_16x16x32_bf16 v[0:3], v[180:183], v[218:221], 0
	v_mfma_f32_16x16x32_bf16 v[52:55], v[176:179], v[198:201], v[52:55]
	v_mfma_f32_16x16x32_bf16 v[48:51], v[190:193], v[198:201], v[48:51]
	v_mfma_f32_16x16x32_bf16 v[36:39], v[176:179], v[206:209], v[36:39]
	v_mfma_f32_16x16x32_bf16 v[32:35], v[190:193], v[206:209], v[32:35]
	v_mfma_f32_16x16x32_bf16 v[20:23], v[176:179], v[214:217], v[20:23]
	v_mfma_f32_16x16x32_bf16 v[16:19], v[190:193], v[214:217], v[16:19]
	v_mfma_f32_16x16x32_bf16 v[4:7], v[176:179], v[222:225], v[4:7]
	v_mfma_f32_16x16x32_bf16 v[0:3], v[190:193], v[222:225], v[0:3]
	s_barrier
	s_setprio 0
	s_add_i32 s64, 0, 0x18000
	v_add_u32_e32 v155, s64, v150
	s_add_i32 s65, 0, 0x1c000
	ds_read_b128 v[156:159], v155
	ds_read_b128 v[160:163], v155 offset:1024
	ds_read_b128 v[164:167], v155 offset:2048
	ds_read_b128 v[168:171], v155 offset:3072
	v_add_u32_e32 v155, s65, v150
	ds_read_b128 v[172:175], v155
	ds_read_b128 v[176:179], v155 offset:1024
	ds_read_b128 v[180:183], v155 offset:2048
	ds_read_b128 v[190:193], v155 offset:3072
	s_add_u32 s58, s58, 0x80000
	s_addc_u32 s59, s59, 0
	s_mov_b32 m0, s9
	v_lshl_add_u64 v[234:235], s[58:59], 0, v[128:129]
	ds_read_b128 v[194:197], v154 offset:32768
	ds_read_b128 v[198:201], v154 offset:33792
	ds_read_b128 v[202:205], v154 offset:34816
	ds_read_b128 v[206:209], v154 offset:35840
	ds_read_b128 v[210:213], v154 offset:36864
	ds_read_b128 v[214:217], v154 offset:37888
	ds_read_b128 v[218:221], v154 offset:38912
	ds_read_b128 v[222:225], v154 offset:39936
	global_load_lds_dwordx4 v[234:235], off
	v_lshl_add_u64 v[234:235], s[58:59], 0, v[132:133]
	s_mov_b32 m0, s11
	s_nop 0
	global_load_lds_dwordx4 v[234:235], off
	s_waitcnt vmcnt(8)
	s_waitcnt lgkmcnt(0)
	s_setprio 1
	s_barrier
	v_mfma_f32_16x16x32_bf16 v[124:127], v[156:159], v[194:197], v[124:127]
	v_mfma_f32_16x16x32_bf16 v[120:123], v[164:167], v[194:197], v[120:123]
	v_mfma_f32_16x16x32_bf16 v[108:111], v[156:159], v[202:205], v[108:111]
	v_mfma_f32_16x16x32_bf16 v[104:107], v[164:167], v[202:205], v[104:107]
	v_mfma_f32_16x16x32_bf16 v[92:95], v[156:159], v[210:213], v[92:95]
	v_mfma_f32_16x16x32_bf16 v[88:91], v[164:167], v[210:213], v[88:91]
	v_mfma_f32_16x16x32_bf16 v[76:79], v[156:159], v[218:221], v[76:79]
	v_mfma_f32_16x16x32_bf16 v[72:75], v[164:167], v[218:221], v[72:75]
	v_mfma_f32_16x16x32_bf16 v[124:127], v[160:163], v[198:201], v[124:127]
	v_mfma_f32_16x16x32_bf16 v[120:123], v[168:171], v[198:201], v[120:123]
	v_mfma_f32_16x16x32_bf16 v[108:111], v[160:163], v[206:209], v[108:111]
	v_mfma_f32_16x16x32_bf16 v[104:107], v[168:171], v[206:209], v[104:107]
	v_mfma_f32_16x16x32_bf16 v[92:95], v[160:163], v[214:217], v[92:95]
	v_mfma_f32_16x16x32_bf16 v[88:91], v[168:171], v[214:217], v[88:91]
	v_mfma_f32_16x16x32_bf16 v[76:79], v[160:163], v[222:225], v[76:79]
	v_mfma_f32_16x16x32_bf16 v[72:75], v[168:171], v[222:225], v[72:75]
	s_setprio 0
	s_setprio 1
	v_mfma_f32_16x16x32_bf16 v[116:119], v[172:175], v[194:197], v[116:119]
	v_mfma_f32_16x16x32_bf16 v[112:115], v[180:183], v[194:197], v[112:115]
	v_mfma_f32_16x16x32_bf16 v[100:103], v[172:175], v[202:205], v[100:103]
	v_mfma_f32_16x16x32_bf16 v[96:99], v[180:183], v[202:205], v[96:99]
	v_mfma_f32_16x16x32_bf16 v[84:87], v[172:175], v[210:213], v[84:87]
	v_mfma_f32_16x16x32_bf16 v[80:83], v[180:183], v[210:213], v[80:83]
	v_mfma_f32_16x16x32_bf16 v[68:71], v[172:175], v[218:221], v[68:71]
	v_mfma_f32_16x16x32_bf16 v[64:67], v[180:183], v[218:221], v[64:67]
	v_mfma_f32_16x16x32_bf16 v[116:119], v[176:179], v[198:201], v[116:119]
	v_mfma_f32_16x16x32_bf16 v[112:115], v[190:193], v[198:201], v[112:115]
	v_mfma_f32_16x16x32_bf16 v[100:103], v[176:179], v[206:209], v[100:103]
	v_mfma_f32_16x16x32_bf16 v[96:99], v[190:193], v[206:209], v[96:99]
	v_mfma_f32_16x16x32_bf16 v[84:87], v[176:179], v[214:217], v[84:87]
	v_mfma_f32_16x16x32_bf16 v[80:83], v[190:193], v[214:217], v[80:83]
	v_mfma_f32_16x16x32_bf16 v[68:71], v[176:179], v[222:225], v[68:71]
	v_mfma_f32_16x16x32_bf16 v[64:67], v[190:193], v[222:225], v[64:67]
	s_barrier
; #define PG8_STAGE(bufoff, gbase, voff) do { _Pragma("unroll") for (int _i = 0; _i < 2; ++_i) \
;         __builtin_amdgcn_global_load_lds((const unsigned*)((const char*)(gbase) + (voff)[_i]), (PG8_LAS unsigned*)(lds + (bufoff) + ldsw + _i * 8192), 16, 0, 0); } while (0)
; #define PG8_LDA(dst, b, h) do { _Pragma("unroll") for (int m = 0; m < 4; ++m) _Pragma("unroll") for (int k = 0; k < 2; ++k) dst[m][k] = *(const PG8_LAS bf16x8*)(lds + PG8_SA(b, h) + aoff + m * 2048 + k * 1024); } while (0)
; #define PG8_MMA(ai, bj, At, Bt) do { __builtin_amdgcn_s_setprio(1); _Pragma("unroll") for (int m = 0; m < 4; ++m) _Pragma("unroll") for (int n = 0; n < 2; ++n) _Pragma("unroll") for (int k = 0; k < 2; ++k) \
;         acc[ai][bj][m][n] = __builtin_amdgcn_mfma_f32_16x16x32_bf16(Bt[n][k], At[m][k], acc[ai][bj][m][n], 0, 0, 0); __builtin_amdgcn_s_setprio(0); } while (0)
; #define PG8_WAIT_V(n) asm volatile("s_waitcnt vmcnt(" #n ")" ::: "memory")
; #define PG8_WAIT_L(n) asm volatile("s_waitcnt lgkmcnt(" #n ")" ::: "memory")
; #define PG8_BAR __builtin_amdgcn_s_barrier()
; #define PG8_SCHED __builtin_amdgcn_sched_barrier(0)
; template <class Epi, class Sched, bool ALIGN_EPI = false, bool SP2 = false>
; __device__ __forceinline__ void gemm_phase(PG8_LAS unsigned char* lds, const Gemm g, const Sched& S, const Epi& E) {
;     ...
;             PG8_LDA(At, 1, 1); PG8_STAGE(PG8_SB(1, 0), b3, voffB); PG8_STAGE(PG8_SB(1, 1), b3 + hstepB, voffB); PG8_STAGE(PG8_SA(1, 0), a3, voffA);
;             PG8_WAIT_V(8); PG8_WAIT_L(0); PG8_BAR; PG8_MMA(1, 0, At, B0); PG8_MMA(1, 1, At, B1); PG8_BAR; PG8_SCHED;
	s_setprio 0
	s_add_i32 s58, s64, s6
	v_lshl_add_u64 v[226:227], v[226:227], 0, s[20:21]
	s_mov_b32 m0, s58
	ds_read_b128 v[194:197], v154 offset:49152
	ds_read_b128 v[198:201], v154 offset:50176
	ds_read_b128 v[202:205], v154 offset:51200
	ds_read_b128 v[206:209], v154 offset:52224
	ds_read_b128 v[210:213], v154 offset:53248
	ds_read_b128 v[214:217], v154 offset:54272
	ds_read_b128 v[218:221], v154 offset:55296
	ds_read_b128 v[222:225], v154 offset:56320
	global_load_lds_dwordx4 v[226:227], off
	s_add_i32 m0, s58, 0x2000
	s_add_u32 s52, s52, 0x80080
	v_lshl_add_u64 v[226:227], v[228:229], 0, s[20:21]
	s_addc_u32 s53, s53, 0
	s_add_i32 s58, s65, s6
	global_load_lds_dwordx4 v[226:227], off
	v_lshl_add_u64 v[226:227], s[52:53], 0, v[130:131]
	s_mov_b32 m0, s58
	s_nop 0
	global_load_lds_dwordx4 v[226:227], off
	v_lshl_add_u64 v[226:227], s[52:53], 0, v[134:135]
	s_add_i32 m0, s58, 0x2000
	s_nop 0
	global_load_lds_dwordx4 v[226:227], off
	v_lshl_add_u64 v[226:227], v[230:231], 0, s[20:21]
	s_mov_b32 m0, s55
	s_nop 0
	global_load_lds_dwordx4 v[226:227], off
	v_lshl_add_u64 v[226:227], v[232:233], 0, s[20:21]
	s_mov_b32 m0, s56
	s_nop 0
	global_load_lds_dwordx4 v[226:227], off
	s_waitcnt vmcnt(8)
	s_waitcnt lgkmcnt(0)
	s_setprio 1
	s_barrier
	v_mfma_f32_16x16x32_bf16 v[60:63], v[156:159], v[194:197], v[60:63]
	v_mfma_f32_16x16x32_bf16 v[56:59], v[164:167], v[194:197], v[56:59]
	v_mfma_f32_16x16x32_bf16 v[44:47], v[156:159], v[202:205], v[44:47]
	v_mfma_f32_16x16x32_bf16 v[40:43], v[164:167], v[202:205], v[40:43]
	v_mfma_f32_16x16x32_bf16 v[28:31], v[156:159], v[210:213], v[28:31]
	v_mfma_f32_16x16x32_bf16 v[24:27], v[164:167], v[210:213], v[24:27]
	v_mfma_f32_16x16x32_bf16 v[12:15], v[156:159], v[218:221], v[12:15]
	v_mfma_f32_16x16x32_bf16 v[8:11], v[164:167], v[218:221], v[8:11]
	v_mfma_f32_16x16x32_bf16 v[60:63], v[160:163], v[198:201], v[60:63]
	v_mfma_f32_16x16x32_bf16 v[56:59], v[168:171], v[198:201], v[56:59]
	v_mfma_f32_16x16x32_bf16 v[44:47], v[160:163], v[206:209], v[44:47]
	v_mfma_f32_16x16x32_bf16 v[40:43], v[168:171], v[206:209], v[40:43]
	v_mfma_f32_16x16x32_bf16 v[28:31], v[160:163], v[214:217], v[28:31]
	v_mfma_f32_16x16x32_bf16 v[24:27], v[168:171], v[214:217], v[24:27]
	v_mfma_f32_16x16x32_bf16 v[12:15], v[160:163], v[222:225], v[12:15]
	v_mfma_f32_16x16x32_bf16 v[8:11], v[168:171], v[222:225], v[8:11]
	s_setprio 0
	s_setprio 1
	v_mfma_f32_16x16x32_bf16 v[52:55], v[172:175], v[194:197], v[52:55]
	v_mfma_f32_16x16x32_bf16 v[48:51], v[180:183], v[194:197], v[48:51]
	v_mfma_f32_16x16x32_bf16 v[36:39], v[172:175], v[202:205], v[36:39]
	v_mfma_f32_16x16x32_bf16 v[32:35], v[180:183], v[202:205], v[32:35]
	v_mfma_f32_16x16x32_bf16 v[20:23], v[172:175], v[210:213], v[20:23]
	v_mfma_f32_16x16x32_bf16 v[16:19], v[180:183], v[210:213], v[16:19]
	v_mfma_f32_16x16x32_bf16 v[4:7], v[172:175], v[218:221], v[4:7]
	v_mfma_f32_16x16x32_bf16 v[0:3], v[180:183], v[218:221], v[0:3]
	v_mfma_f32_16x16x32_bf16 v[52:55], v[176:179], v[198:201], v[52:55]
	v_mfma_f32_16x16x32_bf16 v[48:51], v[190:193], v[198:201], v[48:51]
	v_mfma_f32_16x16x32_bf16 v[36:39], v[176:179], v[206:209], v[36:39]
	v_mfma_f32_16x16x32_bf16 v[32:35], v[190:193], v[206:209], v[32:35]
	v_mfma_f32_16x16x32_bf16 v[20:23], v[176:179], v[214:217], v[20:23]
	v_mfma_f32_16x16x32_bf16 v[16:19], v[190:193], v[214:217], v[16:19]
	v_mfma_f32_16x16x32_bf16 v[4:7], v[176:179], v[222:225], v[4:7]
	v_mfma_f32_16x16x32_bf16 v[0:3], v[190:193], v[222:225], v[0:3]
	s_barrier
	s_setprio 0
	s_add_i32 s63, s63, 2
	s_add_u32 s50, s50, 0x100
	s_addc_u32 s51, s51, 0
	s_add_u32 s39, s39, 0x100
	s_addc_u32 s41, s41, 0
	s_cmp_gt_u32 s63, 29
	s_cbranch_scc1 .Lmy_peel_5_exit
	.p2alignl 6, 3212836864

; #define PG8_STAGE(bufoff, gbase, voff) do { _Pragma("unroll") for (int _i = 0; _i < 2; ++_i) \
;         __builtin_amdgcn_global_load_lds((const unsigned*)((const char*)(gbase) + (voff)[_i]), (PG8_LAS unsigned*)(lds + (bufoff) + ldsw + _i * 8192), 16, 0, 0); } while (0)
; #define PG8_LDA(dst, b, h) do { _Pragma("unroll") for (int m = 0; m < 4; ++m) _Pragma("unroll") for (int k = 0; k < 2; ++k) dst[m][k] = *(const PG8_LAS bf16x8*)(lds + PG8_SA(b, h) + aoff + m * 2048 + k * 1024); } while (0)
; #define PG8_LDB(dst, b, h) do { _Pragma("unroll") for (int n = 0; n < 2; ++n) _Pragma("unroll") for (int k = 0; k < 2; ++k) dst[n][k] = *(const PG8_LAS bf16x8*)(lds + PG8_SB(b, h) + boff + n * 2048 + k * 1024); } while (0)
; #define PG8_WAIT_V(n) asm volatile("s_waitcnt vmcnt(" #n ")" ::: "memory")
; #define PG8_WAIT_L(n) asm volatile("s_waitcnt lgkmcnt(" #n ")" ::: "memory")
; template <class Epi, class Sched, bool ALIGN_EPI = false, bool SP2 = false>
; __device__ __forceinline__ void gemm_phase(PG8_LAS unsigned char* lds, const Gemm g, const Sched& S, const Epi& E) {
;     ...
;         const bool has_next = S.next(ui + 1, nxt);
;         const char* nA = has_next ? (const char*)g.A + (size_t)nxt.pm * tstepA + (size_t)nxt.z * g.azs + (size_t)(nxt.k0 >> 6) * kstA : cA; const char* nB = has_next ? (const char*)g.Bt + (size_t)nxt.pn * tstepB + (size_t)nxt.z * g.bzs + (size_t)nxt.k0 * 2 : cB;
;         const int nt = cur.nt;
;         for (int t = 0; t < nt; t += 2) {
;             const bool last = (t == nt - 2);
;             const char* a1 = cA + (size_t)(t + 1) * kstA;
;             const char* a2 = last ? nA : cA + (size_t)(t + 2) * kstA; const char* b2 = last ? nB : cB + (size_t)(t + 2) * kstep;
;             const char* a3 = a2 + kstA; const char* b3 = b2 + kstep;
;             if (last && has_next) S.a_ready(nxt);
;             if constexpr (SP2) {
;             PG8_LDB(B0, 0, 0); PG8_LDB(B1, 0, 1); PG8_SCHED; PG8_LDA(At, 0, 0); PG8_STAGE(PG8_SA(1, 1), a1 + hstepA, voffA);
;             PG8_WAIT_V(8); PG8_WAIT_L(0); PG8_BAR; PG8_MMA(0, 0, At, B0); PG8_MMA(0, 1, At, B1); PG8_BAR; PG8_SCHED;
;             PG8_LDA(At, 0, 1); PG8_STAGE(PG8_SB(0, 0), b2, voffB); PG8_STAGE(PG8_SB(0, 1), b2 + hstepB, voffB); PG8_STAGE(PG8_SA(0, 0), a2, voffA);
;             PG8_WAIT_V(8); PG8_WAIT_L(0); PG8_BAR; PG8_MMA(1, 0, At, B0); PG8_MMA(1, 1, At, B1); PG8_BAR; PG8_SCHED;
.LBB0_1656:
	s_ashr_i32 s41, s40, 31
	s_lshl_b64 s[4:5], s[40:41], 20
	v_readlane_b32 s12, v254, 41
	v_readlane_b32 s13, v254, 42
	s_add_u32 s48, s12, s4
	s_addc_u32 s49, s13, s5
	s_and_b64 s[4:5], s[44:45], exec
	s_cselect_b32 s4, s49, s51
	s_cselect_b32 s5, s48, s50
	s_ashr_i32 s39, s38, 31
	s_lshl_b64 s[12:13], s[38:39], 20
	s_add_u32 s54, s3, s12
	s_addc_u32 s55, s10, s13
	s_and_b64 s[12:13], s[44:45], exec
	s_cselect_b32 s12, s55, s53
	s_cselect_b32 s13, s54, s52
	s_add_u32 s50, s50, 0x80080
	s_addc_u32 s51, s51, 0
	s_add_u32 s39, s52, 0x100
	s_addc_u32 s41, s53, 0
	s_mov_b32 s63, -2
	ds_read_b128 v[156:159], v152
	ds_read_b128 v[160:163], v152 offset:1024
	ds_read_b128 v[164:167], v152 offset:2048
	ds_read_b128 v[168:171], v152 offset:3072
	ds_read_b128 v[172:175], v153
	ds_read_b128 v[176:179], v153 offset:1024
	ds_read_b128 v[180:183], v153 offset:2048
	ds_read_b128 v[190:193], v153 offset:3072
	s_add_u32 s52, s50, 0xfff80080
	s_addc_u32 s53, s51, -1
	s_cmp_eq_u32 s63, 28
	s_cselect_b32 s59, s4, s53
	s_cselect_b32 s58, s5, s52
	s_cselect_b32 s53, s12, s41
	s_cselect_b32 s52, s13, s39
	v_lshl_add_u64 v[226:227], s[50:51], 0, v[142:143]
	s_add_i32 m0, s7, 0xc000
	ds_read_b128 v[194:197], v154
	ds_read_b128 v[198:201], v154 offset:1024
	ds_read_b128 v[202:205], v154 offset:2048
	ds_read_b128 v[206:209], v154 offset:3072
	ds_read_b128 v[210:213], v154 offset:4096
	ds_read_b128 v[214:217], v154 offset:5120
	ds_read_b128 v[218:221], v154 offset:6144
	ds_read_b128 v[222:225], v154 offset:7168
	global_load_lds_dwordx4 v[226:227], off
	v_lshl_add_u64 v[226:227], s[50:51], 0, v[144:145]
	s_add_i32 m0, s7, 0xe000
	s_nop 0
	global_load_lds_dwordx4 v[226:227], off
	s_waitcnt vmcnt(8)
	s_waitcnt lgkmcnt(0)
	s_setprio 1
	s_barrier
	v_mfma_f32_16x16x32_bf16 v[124:127], v[156:159], v[194:197], 0
	v_mfma_f32_16x16x32_bf16 v[120:123], v[164:167], v[194:197], 0
	v_mfma_f32_16x16x32_bf16 v[108:111], v[156:159], v[202:205], 0
	v_mfma_f32_16x16x32_bf16 v[104:107], v[164:167], v[202:205], 0
	v_mfma_f32_16x16x32_bf16 v[92:95], v[156:159], v[210:213], 0
	v_mfma_f32_16x16x32_bf16 v[88:91], v[164:167], v[210:213], 0
	v_mfma_f32_16x16x32_bf16 v[76:79], v[156:159], v[218:221], 0
	v_mfma_f32_16x16x32_bf16 v[72:75], v[164:167], v[218:221], 0
	v_mfma_f32_16x16x32_bf16 v[124:127], v[160:163], v[198:201], v[124:127]
	v_mfma_f32_16x16x32_bf16 v[120:123], v[168:171], v[198:201], v[120:123]
	v_mfma_f32_16x16x32_bf16 v[108:111], v[160:163], v[206:209], v[108:111]
	v_mfma_f32_16x16x32_bf16 v[104:107], v[168:171], v[206:209], v[104:107]
	v_mfma_f32_16x16x32_bf16 v[92:95], v[160:163], v[214:217], v[92:95]
	v_mfma_f32_16x16x32_bf16 v[88:91], v[168:171], v[214:217], v[88:91]
	v_mfma_f32_16x16x32_bf16 v[76:79], v[160:163], v[222:225], v[76:79]
	v_mfma_f32_16x16x32_bf16 v[72:75], v[168:171], v[222:225], v[72:75]
	s_setprio 0
	s_setprio 1
	v_mfma_f32_16x16x32_bf16 v[116:119], v[172:175], v[194:197], 0
	v_mfma_f32_16x16x32_bf16 v[112:115], v[180:183], v[194:197], 0
	v_mfma_f32_16x16x32_bf16 v[100:103], v[172:175], v[202:205], 0
	v_mfma_f32_16x16x32_bf16 v[96:99], v[180:183], v[202:205], 0
	v_mfma_f32_16x16x32_bf16 v[84:87], v[172:175], v[210:213], 0
	v_mfma_f32_16x16x32_bf16 v[80:83], v[180:183], v[210:213], 0
	v_mfma_f32_16x16x32_bf16 v[68:71], v[172:175], v[218:221], 0
	v_mfma_f32_16x16x32_bf16 v[64:67], v[180:183], v[218:221], 0
	v_mfma_f32_16x16x32_bf16 v[116:119], v[176:179], v[198:201], v[116:119]
	v_mfma_f32_16x16x32_bf16 v[112:115], v[190:193], v[198:201], v[112:115]
	v_mfma_f32_16x16x32_bf16 v[100:103], v[176:179], v[206:209], v[100:103]
	v_mfma_f32_16x16x32_bf16 v[96:99], v[190:193], v[206:209], v[96:99]
	v_mfma_f32_16x16x32_bf16 v[84:87], v[176:179], v[214:217], v[84:87]
	v_mfma_f32_16x16x32_bf16 v[80:83], v[190:193], v[214:217], v[80:83]
	v_mfma_f32_16x16x32_bf16 v[68:71], v[176:179], v[222:225], v[68:71]
	v_mfma_f32_16x16x32_bf16 v[64:67], v[190:193], v[222:225], v[64:67]
	s_barrier
	s_setprio 0
	s_add_i32 s64, s56, s6
	v_lshl_add_u64 v[226:227], s[52:53], 0, v[130:131]
	s_mov_b32 m0, s64
	ds_read_b128 v[194:197], v154 offset:16384
	ds_read_b128 v[198:201], v154 offset:17408
	ds_read_b128 v[202:205], v154 offset:18432
	ds_read_b128 v[206:209], v154 offset:19456
	ds_read_b128 v[210:213], v154 offset:20480
	ds_read_b128 v[214:217], v154 offset:21504
	ds_read_b128 v[218:221], v154 offset:22528
	ds_read_b128 v[222:225], v154 offset:23552
	global_load_lds_dwordx4 v[226:227], off
	s_add_i32 m0, s64, 0x2000
	s_add_u32 s64, s52, 0x80000
	v_lshl_add_u64 v[228:229], s[52:53], 0, v[134:135]
	s_addc_u32 s65, s53, 0
	s_add_i32 s66, s57, s6
	global_load_lds_dwordx4 v[228:229], off
	v_lshl_add_u64 v[230:231], s[64:65], 0, v[130:131]
	s_mov_b32 m0, s66
	v_lshl_add_u64 v[232:233], s[58:59], 0, v[132:133]
	global_load_lds_dwordx4 v[230:231], off
	v_lshl_add_u64 v[230:231], s[64:65], 0, v[134:135]
	s_add_i32 m0, s66, 0x2000
	s_nop 0
	global_load_lds_dwordx4 v[230:231], off
	v_lshl_add_u64 v[230:231], s[58:59], 0, v[128:129]
	s_mov_b32 m0, s7
	s_nop 0
	global_load_lds_dwordx4 v[230:231], off
	s_mov_b32 m0, s8
	s_nop 0
	global_load_lds_dwordx4 v[232:233], off
	s_waitcnt vmcnt(8)
	s_waitcnt lgkmcnt(0)
	s_setprio 1
	s_barrier
; #define PG8_STAGE(bufoff, gbase, voff) do { _Pragma("unroll") for (int _i = 0; _i < 2; ++_i) \
;         __builtin_amdgcn_global_load_lds((const unsigned*)((const char*)(gbase) + (voff)[_i]), (PG8_LAS unsigned*)(lds + (bufoff) + ldsw + _i * 8192), 16, 0, 0); } while (0)
; #define PG8_LDA(dst, b, h) do { _Pragma("unroll") for (int m = 0; m < 4; ++m) _Pragma("unroll") for (int k = 0; k < 2; ++k) dst[m][k] = *(const PG8_LAS bf16x8*)(lds + PG8_SA(b, h) + aoff + m * 2048 + k * 1024); } while (0)
; #define PG8_LDB(dst, b, h) do { _Pragma("unroll") for (int n = 0; n < 2; ++n) _Pragma("unroll") for (int k = 0; k < 2; ++k) dst[n][k] = *(const PG8_LAS bf16x8*)(lds + PG8_SB(b, h) + boff + n * 2048 + k * 1024); } while (0)
; #define PG8_MMA(ai, bj, At, Bt) do { __builtin_amdgcn_s_setprio(1); _Pragma("unroll") for (int m = 0; m < 4; ++m) _Pragma("unroll") for (int n = 0; n < 2; ++n) _Pragma("unroll") for (int k = 0; k < 2; ++k) \
;         acc[ai][bj][m][n] = __builtin_amdgcn_mfma_f32_16x16x32_bf16(Bt[n][k], At[m][k], acc[ai][bj][m][n], 0, 0, 0); __builtin_amdgcn_s_setprio(0); } while (0)
; #define PG8_WAIT_V(n) asm volatile("s_waitcnt vmcnt(" #n ")" ::: "memory")
; #define PG8_WAIT_L(n) asm volatile("s_waitcnt lgkmcnt(" #n ")" ::: "memory")
; #define PG8_BAR __builtin_amdgcn_s_barrier()
; #define PG8_SCHED __builtin_amdgcn_sched_barrier(0)
; template <class Epi, class Sched, bool ALIGN_EPI = false, bool SP2 = false>
; __device__ __forceinline__ void gemm_phase(PG8_LAS unsigned char* lds, const Gemm g, const Sched& S, const Epi& E) {
;     ...
;             PG8_WAIT_V(8); PG8_WAIT_L(0); PG8_BAR; PG8_MMA(1, 0, At, B0); PG8_MMA(1, 1, At, B1); PG8_BAR; PG8_SCHED;
;             PG8_LDB(B0, 1, 0); PG8_LDB(B1, 1, 1); PG8_SCHED; PG8_LDA(At, 1, 0); PG8_STAGE(PG8_SA(0, 1), a2 + hstepA, voffA);
;             PG8_WAIT_V(8); PG8_WAIT_L(0); PG8_BAR; PG8_MMA(0, 0, At, B0); PG8_MMA(0, 1, At, B1); PG8_BAR; PG8_SCHED;
	v_mfma_f32_16x16x32_bf16 v[60:63], v[156:159], v[194:197], 0
	v_mfma_f32_16x16x32_bf16 v[56:59], v[164:167], v[194:197], 0
	v_mfma_f32_16x16x32_bf16 v[44:47], v[156:159], v[202:205], 0
	v_mfma_f32_16x16x32_bf16 v[40:43], v[164:167], v[202:205], 0
	v_mfma_f32_16x16x32_bf16 v[28:31], v[156:159], v[210:213], 0
	v_mfma_f32_16x16x32_bf16 v[24:27], v[164:167], v[210:213], 0
	v_mfma_f32_16x16x32_bf16 v[12:15], v[156:159], v[218:221], 0
	v_mfma_f32_16x16x32_bf16 v[8:11], v[164:167], v[218:221], 0
	v_mfma_f32_16x16x32_bf16 v[60:63], v[160:163], v[198:201], v[60:63]
	v_mfma_f32_16x16x32_bf16 v[56:59], v[168:171], v[198:201], v[56:59]
	v_mfma_f32_16x16x32_bf16 v[44:47], v[160:163], v[206:209], v[44:47]
	v_mfma_f32_16x16x32_bf16 v[40:43], v[168:171], v[206:209], v[40:43]
	v_mfma_f32_16x16x32_bf16 v[28:31], v[160:163], v[214:217], v[28:31]
	v_mfma_f32_16x16x32_bf16 v[24:27], v[168:171], v[214:217], v[24:27]
	v_mfma_f32_16x16x32_bf16 v[12:15], v[160:163], v[222:225], v[12:15]
	v_mfma_f32_16x16x32_bf16 v[8:11], v[168:171], v[222:225], v[8:11]
	s_setprio 0
	s_setprio 1
	v_mfma_f32_16x16x32_bf16 v[52:55], v[172:175], v[194:197], 0
	v_mfma_f32_16x16x32_bf16 v[48:51], v[180:183], v[194:197], 0
	v_mfma_f32_16x16x32_bf16 v[36:39], v[172:175], v[202:205], 0
	v_mfma_f32_16x16x32_bf16 v[32:35], v[180:183], v[202:205], 0
	v_mfma_f32_16x16x32_bf16 v[20:23], v[172:175], v[210:213], 0
	v_mfma_f32_16x16x32_bf16 v[16:19], v[180:183], v[210:213], 0
	v_mfma_f32_16x16x32_bf16 v[4:7], v[172:175], v[218:221], 0
	v_mfma_f32_16x16x32_bf16 v[0:3], v[180:183], v[218:221], 0
	v_mfma_f32_16x16x32_bf16 v[52:55], v[176:179], v[198:201], v[52:55]
	v_mfma_f32_16x16x32_bf16 v[48:51], v[190:193], v[198:201], v[48:51]
	v_mfma_f32_16x16x32_bf16 v[36:39], v[176:179], v[206:209], v[36:39]
	v_mfma_f32_16x16x32_bf16 v[32:35], v[190:193], v[206:209], v[32:35]
	v_mfma_f32_16x16x32_bf16 v[20:23], v[176:179], v[214:217], v[20:23]
	v_mfma_f32_16x16x32_bf16 v[16:19], v[190:193], v[214:217], v[16:19]
	v_mfma_f32_16x16x32_bf16 v[4:7], v[176:179], v[222:225], v[4:7]
	v_mfma_f32_16x16x32_bf16 v[0:3], v[190:193], v[222:225], v[0:3]
	s_barrier
	s_setprio 0
	s_add_i32 s64, 0, 0x18000
	v_add_u32_e32 v155, s64, v150
	s_add_i32 s65, 0, 0x1c000
	ds_read_b128 v[156:159], v155
	ds_read_b128 v[160:163], v155 offset:1024
	ds_read_b128 v[164:167], v155 offset:2048
	ds_read_b128 v[168:171], v155 offset:3072
	v_add_u32_e32 v155, s65, v150
	ds_read_b128 v[172:175], v155
	ds_read_b128 v[176:179], v155 offset:1024
	ds_read_b128 v[180:183], v155 offset:2048
	ds_read_b128 v[190:193], v155 offset:3072
	s_add_u32 s58, s58, 0x80000
	s_addc_u32 s59, s59, 0
	s_mov_b32 m0, s9
	v_lshl_add_u64 v[234:235], s[58:59], 0, v[128:129]
	ds_read_b128 v[194:197], v154 offset:32768
	ds_read_b128 v[198:201], v154 offset:33792
	ds_read_b128 v[202:205], v154 offset:34816
	ds_read_b128 v[206:209], v154 offset:35840
	ds_read_b128 v[210:213], v154 offset:36864
	ds_read_b128 v[214:217], v154 offset:37888
	ds_read_b128 v[218:221], v154 offset:38912
	ds_read_b128 v[222:225], v154 offset:39936
	global_load_lds_dwordx4 v[234:235], off
	v_lshl_add_u64 v[234:235], s[58:59], 0, v[132:133]
	s_mov_b32 m0, s11
	s_nop 0
	global_load_lds_dwordx4 v[234:235], off
	s_waitcnt vmcnt(8)
	s_waitcnt lgkmcnt(0)
	s_setprio 1
	s_barrier
	v_mfma_f32_16x16x32_bf16 v[124:127], v[156:159], v[194:197], v[124:127]
	v_mfma_f32_16x16x32_bf16 v[120:123], v[164:167], v[194:197], v[120:123]
	v_mfma_f32_16x16x32_bf16 v[108:111], v[156:159], v[202:205], v[108:111]
	v_mfma_f32_16x16x32_bf16 v[104:107], v[164:167], v[202:205], v[104:107]
	v_mfma_f32_16x16x32_bf16 v[92:95], v[156:159], v[210:213], v[92:95]
	v_mfma_f32_16x16x32_bf16 v[88:91], v[164:167], v[210:213], v[88:91]
	v_mfma_f32_16x16x32_bf16 v[76:79], v[156:159], v[218:221], v[76:79]
	v_mfma_f32_16x16x32_bf16 v[72:75], v[164:167], v[218:221], v[72:75]
	v_mfma_f32_16x16x32_bf16 v[124:127], v[160:163], v[198:201], v[124:127]
	v_mfma_f32_16x16x32_bf16 v[120:123], v[168:171], v[198:201], v[120:123]
	v_mfma_f32_16x16x32_bf16 v[108:111], v[160:163], v[206:209], v[108:111]
	v_mfma_f32_16x16x32_bf16 v[104:107], v[168:171], v[206:209], v[104:107]
	v_mfma_f32_16x16x32_bf16 v[92:95], v[160:163], v[214:217], v[92:95]
	v_mfma_f32_16x16x32_bf16 v[88:91], v[168:171], v[214:217], v[88:91]
	v_mfma_f32_16x16x32_bf16 v[76:79], v[160:163], v[222:225], v[76:79]
	v_mfma_f32_16x16x32_bf16 v[72:75], v[168:171], v[222:225], v[72:75]
	s_setprio 0
	s_setprio 1
	v_mfma_f32_16x16x32_bf16 v[116:119], v[172:175], v[194:197], v[116:119]
	v_mfma_f32_16x16x32_bf16 v[112:115], v[180:183], v[194:197], v[112:115]
	v_mfma_f32_16x16x32_bf16 v[100:103], v[172:175], v[202:205], v[100:103]
	v_mfma_f32_16x16x32_bf16 v[96:99], v[180:183], v[202:205], v[96:99]
	v_mfma_f32_16x16x32_bf16 v[84:87], v[172:175], v[210:213], v[84:87]
	v_mfma_f32_16x16x32_bf16 v[80:83], v[180:183], v[210:213], v[80:83]
	v_mfma_f32_16x16x32_bf16 v[68:71], v[172:175], v[218:221], v[68:71]
	v_mfma_f32_16x16x32_bf16 v[64:67], v[180:183], v[218:221], v[64:67]
	v_mfma_f32_16x16x32_bf16 v[116:119], v[176:179], v[198:201], v[116:119]
	v_mfma_f32_16x16x32_bf16 v[112:115], v[190:193], v[198:201], v[112:115]
	v_mfma_f32_16x16x32_bf16 v[100:103], v[176:179], v[206:209], v[100:103]
	v_mfma_f32_16x16x32_bf16 v[96:99], v[190:193], v[206:209], v[96:99]
	v_mfma_f32_16x16x32_bf16 v[84:87], v[176:179], v[214:217], v[84:87]
	v_mfma_f32_16x16x32_bf16 v[80:83], v[190:193], v[214:217], v[80:83]
	v_mfma_f32_16x16x32_bf16 v[68:71], v[176:179], v[222:225], v[68:71]
	v_mfma_f32_16x16x32_bf16 v[64:67], v[190:193], v[222:225], v[64:67]
	s_barrier
; #define PG8_STAGE(bufoff, gbase, voff) do { _Pragma("unroll") for (int _i = 0; _i < 2; ++_i) \
;         __builtin_amdgcn_global_load_lds((const unsigned*)((const char*)(gbase) + (voff)[_i]), (PG8_LAS unsigned*)(lds + (bufoff) + ldsw + _i * 8192), 16, 0, 0); } while (0)
; #define PG8_LDA(dst, b, h) do { _Pragma("unroll") for (int m = 0; m < 4; ++m) _Pragma("unroll") for (int k = 0; k < 2; ++k) dst[m][k] = *(const PG8_LAS bf16x8*)(lds + PG8_SA(b, h) + aoff + m * 2048 + k * 1024); } while (0)
; #define PG8_MMA(ai, bj, At, Bt) do { __builtin_amdgcn_s_setprio(1); _Pragma("unroll") for (int m = 0; m < 4; ++m) _Pragma("unroll") for (int n = 0; n < 2; ++n) _Pragma("unroll") for (int k = 0; k < 2; ++k) \
;         acc[ai][bj][m][n] = __builtin_amdgcn_mfma_f32_16x16x32_bf16(Bt[n][k], At[m][k], acc[ai][bj][m][n], 0, 0, 0); __builtin_amdgcn_s_setprio(0); } while (0)
; #define PG8_WAIT_V(n) asm volatile("s_waitcnt vmcnt(" #n ")" ::: "memory")
; #define PG8_WAIT_L(n) asm volatile("s_waitcnt lgkmcnt(" #n ")" ::: "memory")
; #define PG8_BAR __builtin_amdgcn_s_barrier()
; #define PG8_SCHED __builtin_amdgcn_sched_barrier(0)
; template <class Epi, class Sched, bool ALIGN_EPI = false, bool SP2 = false>
; __device__ __forceinline__ void gemm_phase(PG8_LAS unsigned char* lds, const Gemm g, const Sched& S, const Epi& E) {
;     ...
;             PG8_LDA(At, 1, 1); PG8_STAGE(PG8_SB(1, 0), b3, voffB); PG8_STAGE(PG8_SB(1, 1), b3 + hstepB, voffB); PG8_STAGE(PG8_SA(1, 0), a3, voffA);
;             PG8_WAIT_V(8); PG8_WAIT_L(0); PG8_BAR; PG8_MMA(1, 0, At, B0); PG8_MMA(1, 1, At, B1); PG8_BAR; PG8_SCHED;
	s_setprio 0
	s_add_i32 s58, s64, s6
	v_lshl_add_u64 v[226:227], v[226:227], 0, s[20:21]
	s_mov_b32 m0, s58
	ds_read_b128 v[194:197], v154 offset:49152
	ds_read_b128 v[198:201], v154 offset:50176
	ds_read_b128 v[202:205], v154 offset:51200
	ds_read_b128 v[206:209], v154 offset:52224
	ds_read_b128 v[210:213], v154 offset:53248
	ds_read_b128 v[214:217], v154 offset:54272
	ds_read_b128 v[218:221], v154 offset:55296
	ds_read_b128 v[222:225], v154 offset:56320
	global_load_lds_dwordx4 v[226:227], off
	s_add_i32 m0, s58, 0x2000
	s_add_u32 s52, s52, 0x80080
	v_lshl_add_u64 v[226:227], v[228:229], 0, s[20:21]
	s_addc_u32 s53, s53, 0
	s_add_i32 s58, s65, s6
	global_load_lds_dwordx4 v[226:227], off
	v_lshl_add_u64 v[226:227], s[52:53], 0, v[130:131]
	s_mov_b32 m0, s58
	s_nop 0
	global_load_lds_dwordx4 v[226:227], off
	v_lshl_add_u64 v[226:227], s[52:53], 0, v[134:135]
	s_add_i32 m0, s58, 0x2000
	s_nop 0
	global_load_lds_dwordx4 v[226:227], off
	v_lshl_add_u64 v[226:227], v[230:231], 0, s[20:21]
	s_mov_b32 m0, s46
	s_nop 0
	global_load_lds_dwordx4 v[226:227], off
	v_lshl_add_u64 v[226:227], v[232:233], 0, s[20:21]
	s_mov_b32 m0, s47
	s_nop 0
	global_load_lds_dwordx4 v[226:227], off
	s_waitcnt vmcnt(8)
	s_waitcnt lgkmcnt(0)
	s_setprio 1
	s_barrier
	v_mfma_f32_16x16x32_bf16 v[60:63], v[156:159], v[194:197], v[60:63]
	v_mfma_f32_16x16x32_bf16 v[56:59], v[164:167], v[194:197], v[56:59]
	v_mfma_f32_16x16x32_bf16 v[44:47], v[156:159], v[202:205], v[44:47]
	v_mfma_f32_16x16x32_bf16 v[40:43], v[164:167], v[202:205], v[40:43]
	v_mfma_f32_16x16x32_bf16 v[28:31], v[156:159], v[210:213], v[28:31]
	v_mfma_f32_16x16x32_bf16 v[24:27], v[164:167], v[210:213], v[24:27]
	v_mfma_f32_16x16x32_bf16 v[12:15], v[156:159], v[218:221], v[12:15]
	v_mfma_f32_16x16x32_bf16 v[8:11], v[164:167], v[218:221], v[8:11]
	v_mfma_f32_16x16x32_bf16 v[60:63], v[160:163], v[198:201], v[60:63]
	v_mfma_f32_16x16x32_bf16 v[56:59], v[168:171], v[198:201], v[56:59]
	v_mfma_f32_16x16x32_bf16 v[44:47], v[160:163], v[206:209], v[44:47]
	v_mfma_f32_16x16x32_bf16 v[40:43], v[168:171], v[206:209], v[40:43]
	v_mfma_f32_16x16x32_bf16 v[28:31], v[160:163], v[214:217], v[28:31]
	v_mfma_f32_16x16x32_bf16 v[24:27], v[168:171], v[214:217], v[24:27]
	v_mfma_f32_16x16x32_bf16 v[12:15], v[160:163], v[222:225], v[12:15]
	v_mfma_f32_16x16x32_bf16 v[8:11], v[168:171], v[222:225], v[8:11]
	s_setprio 0
	s_setprio 1
	v_mfma_f32_16x16x32_bf16 v[52:55], v[172:175], v[194:197], v[52:55]
	v_mfma_f32_16x16x32_bf16 v[48:51], v[180:183], v[194:197], v[48:51]
	v_mfma_f32_16x16x32_bf16 v[36:39], v[172:175], v[202:205], v[36:39]
	v_mfma_f32_16x16x32_bf16 v[32:35], v[180:183], v[202:205], v[32:35]
	v_mfma_f32_16x16x32_bf16 v[20:23], v[172:175], v[210:213], v[20:23]
	v_mfma_f32_16x16x32_bf16 v[16:19], v[180:183], v[210:213], v[16:19]
	v_mfma_f32_16x16x32_bf16 v[4:7], v[172:175], v[218:221], v[4:7]
	v_mfma_f32_16x16x32_bf16 v[0:3], v[180:183], v[218:221], v[0:3]
	v_mfma_f32_16x16x32_bf16 v[52:55], v[176:179], v[198:201], v[52:55]
	v_mfma_f32_16x16x32_bf16 v[48:51], v[190:193], v[198:201], v[48:51]
	v_mfma_f32_16x16x32_bf16 v[36:39], v[176:179], v[206:209], v[36:39]
	v_mfma_f32_16x16x32_bf16 v[32:35], v[190:193], v[206:209], v[32:35]
	v_mfma_f32_16x16x32_bf16 v[20:23], v[176:179], v[214:217], v[20:23]
	v_mfma_f32_16x16x32_bf16 v[16:19], v[190:193], v[214:217], v[16:19]
	v_mfma_f32_16x16x32_bf16 v[4:7], v[176:179], v[222:225], v[4:7]
	v_mfma_f32_16x16x32_bf16 v[0:3], v[190:193], v[222:225], v[0:3]
	s_barrier
	s_setprio 0
	s_add_i32 s63, s63, 2
	s_add_u32 s50, s50, 0x100
	s_addc_u32 s51, s51, 0
	s_add_u32 s39, s39, 0x100
	s_addc_u32 s41, s41, 0
	s_cmp_gt_u32 s63, 29
	s_cbranch_scc1 .Lmy_peel_7_exit
	.p2alignl 6, 3212836864

; #define PG8_STAGE(bufoff, gbase, voff) do { _Pragma("unroll") for (int _i = 0; _i < 2; ++_i) \
;         __builtin_amdgcn_global_load_lds((const unsigned*)((const char*)(gbase) + (voff)[_i]), (PG8_LAS unsigned*)(lds + (bufoff) + ldsw + _i * 8192), 16, 0, 0); } while (0)
; #define PG8_LDA(dst, b, h) do { _Pragma("unroll") for (int m = 0; m < 4; ++m) _Pragma("unroll") for (int k = 0; k < 2; ++k) dst[m][k] = *(const PG8_LAS bf16x8*)(lds + PG8_SA(b, h) + aoff + m * 2048 + k * 1024); } while (0)
; #define PG8_LDB(dst, b, h) do { _Pragma("unroll") for (int n = 0; n < 2; ++n) _Pragma("unroll") for (int k = 0; k < 2; ++k) dst[n][k] = *(const PG8_LAS bf16x8*)(lds + PG8_SB(b, h) + boff + n * 2048 + k * 1024); } while (0)
; #define PG8_WAIT_V(n) asm volatile("s_waitcnt vmcnt(" #n ")" ::: "memory")
; #define PG8_WAIT_L(n) asm volatile("s_waitcnt lgkmcnt(" #n ")" ::: "memory")
; template <class Epi, class Sched, bool ALIGN_EPI = false, bool SP2 = false>
; __device__ __forceinline__ void gemm_phase(PG8_LAS unsigned char* lds, const Gemm g, const Sched& S, const Epi& E) {
;     ...
;         const bool has_next = S.next(ui + 1, nxt);
;         const char* nA = has_next ? (const char*)g.A + (size_t)nxt.pm * tstepA + (size_t)nxt.z * g.azs + (size_t)(nxt.k0 >> 6) * kstA : cA; const char* nB = has_next ? (const char*)g.Bt + (size_t)nxt.pn * tstepB + (size_t)nxt.z * g.bzs + (size_t)nxt.k0 * 2 : cB;
;         const int nt = cur.nt;
;         for (int t = 0; t < nt; t += 2) {
;             const bool last = (t == nt - 2);
;             const char* a1 = cA + (size_t)(t + 1) * kstA;
;             const char* a2 = last ? nA : cA + (size_t)(t + 2) * kstA; const char* b2 = last ? nB : cB + (size_t)(t + 2) * kstep;
;             const char* a3 = a2 + kstA; const char* b3 = b2 + kstep;
;             if (last && has_next) S.a_ready(nxt);
;             if constexpr (SP2) {
;             PG8_LDB(B0, 0, 0); PG8_LDB(B1, 0, 1); PG8_SCHED; PG8_LDA(At, 0, 0); PG8_STAGE(PG8_SA(1, 1), a1 + hstepA, voffA);
;             PG8_WAIT_V(8); PG8_WAIT_L(0); PG8_BAR; PG8_MMA(0, 0, At, B0); PG8_MMA(0, 1, At, B1); PG8_BAR; PG8_SCHED;
;             PG8_LDA(At, 0, 1); PG8_STAGE(PG8_SB(0, 0), b2, voffB); PG8_STAGE(PG8_SB(0, 1), b2 + hstepB, voffB); PG8_STAGE(PG8_SA(0, 0), a2, voffA);
;             PG8_WAIT_V(8); PG8_WAIT_L(0); PG8_BAR; PG8_MMA(1, 0, At, B0); PG8_MMA(1, 1, At, B1); PG8_BAR; PG8_SCHED;
.LBB0_2049:
	s_ashr_i32 s61, s60, 31
	s_lshl_b64 s[4:5], s[60:61], 20
	v_readlane_b32 s10, v254, 41
	v_readlane_b32 s11, v254, 42
	s_add_u32 s62, s10, s4
	s_addc_u32 s63, s11, s5
	s_and_b64 s[4:5], s[42:43], exec
	s_cselect_b32 s1, s63, s21
	s_cselect_b32 s3, s62, s20
	s_ashr_i32 s59, s58, 31
	s_lshl_b64 s[4:5], s[58:59], 20
	s_add_u32 s64, s72, s4
	s_addc_u32 s65, s73, s5
	s_and_b64 s[4:5], s[42:43], exec
	s_cselect_b32 s4, s65, s39
	s_cselect_b32 s5, s64, s38
	s_add_u32 s20, s20, 0x80080
	s_addc_u32 s21, s21, 0
	s_add_u32 s10, s38, 0x100
	s_addc_u32 s11, s39, 0
	s_mov_b32 s12, -2
	ds_read_b128 v[128:131], v159
	ds_read_b128 v[132:135], v159 offset:1024
	ds_read_b128 v[164:167], v159 offset:2048
	ds_read_b128 v[168:171], v159 offset:3072
	ds_read_b128 v[172:175], v160
	ds_read_b128 v[176:179], v160 offset:1024
	ds_read_b128 v[180:183], v160 offset:2048
	ds_read_b128 v[190:193], v160 offset:3072
	s_add_u32 s13, s20, 0xfff80080
	s_addc_u32 s33, s21, -1
	s_cmp_eq_u32 s12, 28
	s_cselect_b32 s41, s1, s33
	s_cselect_b32 s40, s3, s13
	s_cselect_b32 s39, s4, s11
	s_cselect_b32 s38, s5, s10
	v_lshl_add_u64 v[226:227], s[20:21], 0, v[148:149]
	s_add_i32 m0, s7, 0xc000
	ds_read_b128 v[194:197], v161
	ds_read_b128 v[198:201], v161 offset:1024
	ds_read_b128 v[202:205], v161 offset:2048
	ds_read_b128 v[206:209], v161 offset:3072
	ds_read_b128 v[210:213], v161 offset:4096
	ds_read_b128 v[214:217], v161 offset:5120
	ds_read_b128 v[218:221], v161 offset:6144
	ds_read_b128 v[222:225], v161 offset:7168
	global_load_lds_dwordx4 v[226:227], off
	v_lshl_add_u64 v[226:227], s[20:21], 0, v[150:151]
	s_add_i32 m0, s7, 0xe000
	s_nop 0
	global_load_lds_dwordx4 v[226:227], off
	s_waitcnt vmcnt(8)
	s_waitcnt lgkmcnt(0)
	s_setprio 1
	s_barrier
	v_mfma_f32_16x16x32_bf16 v[124:127], v[128:131], v[194:197], 0
	v_mfma_f32_16x16x32_bf16 v[120:123], v[164:167], v[194:197], 0
	v_mfma_f32_16x16x32_bf16 v[108:111], v[128:131], v[202:205], 0
	v_mfma_f32_16x16x32_bf16 v[104:107], v[164:167], v[202:205], 0
	v_mfma_f32_16x16x32_bf16 v[92:95], v[128:131], v[210:213], 0
	v_mfma_f32_16x16x32_bf16 v[88:91], v[164:167], v[210:213], 0
	v_mfma_f32_16x16x32_bf16 v[76:79], v[128:131], v[218:221], 0
	v_mfma_f32_16x16x32_bf16 v[72:75], v[164:167], v[218:221], 0
	v_mfma_f32_16x16x32_bf16 v[124:127], v[132:135], v[198:201], v[124:127]
	v_mfma_f32_16x16x32_bf16 v[120:123], v[168:171], v[198:201], v[120:123]
	v_mfma_f32_16x16x32_bf16 v[108:111], v[132:135], v[206:209], v[108:111]
	v_mfma_f32_16x16x32_bf16 v[104:107], v[168:171], v[206:209], v[104:107]
	v_mfma_f32_16x16x32_bf16 v[92:95], v[132:135], v[214:217], v[92:95]
	v_mfma_f32_16x16x32_bf16 v[88:91], v[168:171], v[214:217], v[88:91]
	v_mfma_f32_16x16x32_bf16 v[76:79], v[132:135], v[222:225], v[76:79]
	v_mfma_f32_16x16x32_bf16 v[72:75], v[168:171], v[222:225], v[72:75]
	s_setprio 0
	s_setprio 1
	v_mfma_f32_16x16x32_bf16 v[116:119], v[172:175], v[194:197], 0
	v_mfma_f32_16x16x32_bf16 v[112:115], v[180:183], v[194:197], 0
	v_mfma_f32_16x16x32_bf16 v[100:103], v[172:175], v[202:205], 0
	v_mfma_f32_16x16x32_bf16 v[96:99], v[180:183], v[202:205], 0
	v_mfma_f32_16x16x32_bf16 v[84:87], v[172:175], v[210:213], 0
	v_mfma_f32_16x16x32_bf16 v[80:83], v[180:183], v[210:213], 0
	v_mfma_f32_16x16x32_bf16 v[68:71], v[172:175], v[218:221], 0
	v_mfma_f32_16x16x32_bf16 v[64:67], v[180:183], v[218:221], 0
	v_mfma_f32_16x16x32_bf16 v[116:119], v[176:179], v[198:201], v[116:119]
	v_mfma_f32_16x16x32_bf16 v[112:115], v[190:193], v[198:201], v[112:115]
	v_mfma_f32_16x16x32_bf16 v[100:103], v[176:179], v[206:209], v[100:103]
	v_mfma_f32_16x16x32_bf16 v[96:99], v[190:193], v[206:209], v[96:99]
	v_mfma_f32_16x16x32_bf16 v[84:87], v[176:179], v[214:217], v[84:87]
	v_mfma_f32_16x16x32_bf16 v[80:83], v[190:193], v[214:217], v[80:83]
	v_mfma_f32_16x16x32_bf16 v[68:71], v[176:179], v[222:225], v[68:71]
	v_mfma_f32_16x16x32_bf16 v[64:67], v[190:193], v[222:225], v[64:67]
	s_barrier
	s_setprio 0
	s_add_i32 s13, s69, s6
	v_lshl_add_u64 v[226:227], s[38:39], 0, v[138:139]
	s_mov_b32 m0, s13
	ds_read_b128 v[194:197], v161 offset:16384
	ds_read_b128 v[198:201], v161 offset:17408
	ds_read_b128 v[202:205], v161 offset:18432
	ds_read_b128 v[206:209], v161 offset:19456
	ds_read_b128 v[210:213], v161 offset:20480
	ds_read_b128 v[214:217], v161 offset:21504
	ds_read_b128 v[218:221], v161 offset:22528
	ds_read_b128 v[222:225], v161 offset:23552
	global_load_lds_dwordx4 v[226:227], off
	s_add_i32 m0, s13, 0x2000
	s_add_u32 s44, s38, 0x80000
	v_lshl_add_u64 v[228:229], s[38:39], 0, v[142:143]
	s_addc_u32 s45, s39, 0
	s_add_i32 s13, s70, s6
	global_load_lds_dwordx4 v[228:229], off
	v_lshl_add_u64 v[230:231], s[44:45], 0, v[138:139]
	s_mov_b32 m0, s13
	v_lshl_add_u64 v[232:233], s[40:41], 0, v[140:141]
	global_load_lds_dwordx4 v[230:231], off
	v_lshl_add_u64 v[230:231], s[44:45], 0, v[142:143]
	s_add_i32 m0, s13, 0x2000
	s_nop 0
	global_load_lds_dwordx4 v[230:231], off
	v_lshl_add_u64 v[230:231], s[40:41], 0, v[136:137]
	s_mov_b32 m0, s7
	s_nop 0
	global_load_lds_dwordx4 v[230:231], off
	s_mov_b32 m0, s8
	s_nop 0
	global_load_lds_dwordx4 v[232:233], off
	s_waitcnt vmcnt(8)
	s_waitcnt lgkmcnt(0)
	s_setprio 1
	s_barrier
; #define PG8_STAGE(bufoff, gbase, voff) do { _Pragma("unroll") for (int _i = 0; _i < 2; ++_i) \
;         __builtin_amdgcn_global_load_lds((const unsigned*)((const char*)(gbase) + (voff)[_i]), (PG8_LAS unsigned*)(lds + (bufoff) + ldsw + _i * 8192), 16, 0, 0); } while (0)
; #define PG8_LDA(dst, b, h) do { _Pragma("unroll") for (int m = 0; m < 4; ++m) _Pragma("unroll") for (int k = 0; k < 2; ++k) dst[m][k] = *(const PG8_LAS bf16x8*)(lds + PG8_SA(b, h) + aoff + m * 2048 + k * 1024); } while (0)
; #define PG8_LDB(dst, b, h) do { _Pragma("unroll") for (int n = 0; n < 2; ++n) _Pragma("unroll") for (int k = 0; k < 2; ++k) dst[n][k] = *(const PG8_LAS bf16x8*)(lds + PG8_SB(b, h) + boff + n * 2048 + k * 1024); } while (0)
; #define PG8_MMA(ai, bj, At, Bt) do { __builtin_amdgcn_s_setprio(1); _Pragma("unroll") for (int m = 0; m < 4; ++m) _Pragma("unroll") for (int n = 0; n < 2; ++n) _Pragma("unroll") for (int k = 0; k < 2; ++k) \
;         acc[ai][bj][m][n] = __builtin_amdgcn_mfma_f32_16x16x32_bf16(Bt[n][k], At[m][k], acc[ai][bj][m][n], 0, 0, 0); __builtin_amdgcn_s_setprio(0); } while (0)
; #define PG8_WAIT_V(n) asm volatile("s_waitcnt vmcnt(" #n ")" ::: "memory")
; #define PG8_WAIT_L(n) asm volatile("s_waitcnt lgkmcnt(" #n ")" ::: "memory")
; #define PG8_BAR __builtin_amdgcn_s_barrier()
; #define PG8_SCHED __builtin_amdgcn_sched_barrier(0)
; template <class Epi, class Sched, bool ALIGN_EPI = false, bool SP2 = false>
; __device__ __forceinline__ void gemm_phase(PG8_LAS unsigned char* lds, const Gemm g, const Sched& S, const Epi& E) {
;     ...
;             PG8_WAIT_V(8); PG8_WAIT_L(0); PG8_BAR; PG8_MMA(1, 0, At, B0); PG8_MMA(1, 1, At, B1); PG8_BAR; PG8_SCHED;
;             PG8_LDB(B0, 1, 0); PG8_LDB(B1, 1, 1); PG8_SCHED; PG8_LDA(At, 1, 0); PG8_STAGE(PG8_SA(0, 1), a2 + hstepA, voffA);
;             PG8_WAIT_V(8); PG8_WAIT_L(0); PG8_BAR; PG8_MMA(0, 0, At, B0); PG8_MMA(0, 1, At, B1); PG8_BAR; PG8_SCHED;
	v_mfma_f32_16x16x32_bf16 v[60:63], v[128:131], v[194:197], 0
	v_mfma_f32_16x16x32_bf16 v[56:59], v[164:167], v[194:197], 0
	v_mfma_f32_16x16x32_bf16 v[44:47], v[128:131], v[202:205], 0
	v_mfma_f32_16x16x32_bf16 v[40:43], v[164:167], v[202:205], 0
	v_mfma_f32_16x16x32_bf16 v[28:31], v[128:131], v[210:213], 0
	v_mfma_f32_16x16x32_bf16 v[24:27], v[164:167], v[210:213], 0
	v_mfma_f32_16x16x32_bf16 v[12:15], v[128:131], v[218:221], 0
	v_mfma_f32_16x16x32_bf16 v[8:11], v[164:167], v[218:221], 0
	v_mfma_f32_16x16x32_bf16 v[60:63], v[132:135], v[198:201], v[60:63]
	v_mfma_f32_16x16x32_bf16 v[56:59], v[168:171], v[198:201], v[56:59]
	v_mfma_f32_16x16x32_bf16 v[44:47], v[132:135], v[206:209], v[44:47]
	v_mfma_f32_16x16x32_bf16 v[40:43], v[168:171], v[206:209], v[40:43]
	v_mfma_f32_16x16x32_bf16 v[28:31], v[132:135], v[214:217], v[28:31]
	v_mfma_f32_16x16x32_bf16 v[24:27], v[168:171], v[214:217], v[24:27]
	v_mfma_f32_16x16x32_bf16 v[12:15], v[132:135], v[222:225], v[12:15]
	v_mfma_f32_16x16x32_bf16 v[8:11], v[168:171], v[222:225], v[8:11]
	s_setprio 0
	s_setprio 1
	v_mfma_f32_16x16x32_bf16 v[52:55], v[172:175], v[194:197], 0
	v_mfma_f32_16x16x32_bf16 v[48:51], v[180:183], v[194:197], 0
	v_mfma_f32_16x16x32_bf16 v[36:39], v[172:175], v[202:205], 0
	v_mfma_f32_16x16x32_bf16 v[32:35], v[180:183], v[202:205], 0
	v_mfma_f32_16x16x32_bf16 v[20:23], v[172:175], v[210:213], 0
	v_mfma_f32_16x16x32_bf16 v[16:19], v[180:183], v[210:213], 0
	v_mfma_f32_16x16x32_bf16 v[4:7], v[172:175], v[218:221], 0
	v_mfma_f32_16x16x32_bf16 v[0:3], v[180:183], v[218:221], 0
	v_mfma_f32_16x16x32_bf16 v[52:55], v[176:179], v[198:201], v[52:55]
	v_mfma_f32_16x16x32_bf16 v[48:51], v[190:193], v[198:201], v[48:51]
	v_mfma_f32_16x16x32_bf16 v[36:39], v[176:179], v[206:209], v[36:39]
	v_mfma_f32_16x16x32_bf16 v[32:35], v[190:193], v[206:209], v[32:35]
	v_mfma_f32_16x16x32_bf16 v[20:23], v[176:179], v[214:217], v[20:23]
	v_mfma_f32_16x16x32_bf16 v[16:19], v[190:193], v[214:217], v[16:19]
	v_mfma_f32_16x16x32_bf16 v[4:7], v[176:179], v[222:225], v[4:7]
	v_mfma_f32_16x16x32_bf16 v[0:3], v[190:193], v[222:225], v[0:3]
	s_barrier
	s_setprio 0
	s_add_i32 s13, 0, 0x18000
	v_add_u32_e32 v144, s13, v157
	s_add_i32 s33, 0, 0x1c000
	ds_read_b128 v[128:131], v144
	ds_read_b128 v[132:135], v144 offset:1024
	ds_read_b128 v[164:167], v144 offset:2048
	ds_read_b128 v[168:171], v144 offset:3072
	v_add_u32_e32 v144, s33, v157
	ds_read_b128 v[172:175], v144
	ds_read_b128 v[176:179], v144 offset:1024
	ds_read_b128 v[180:183], v144 offset:2048
	ds_read_b128 v[190:193], v144 offset:3072
	s_add_u32 s40, s40, 0x80000
	s_addc_u32 s41, s41, 0
	s_mov_b32 m0, s9
	v_lshl_add_u64 v[234:235], s[40:41], 0, v[136:137]
	ds_read_b128 v[194:197], v161 offset:32768
	ds_read_b128 v[198:201], v161 offset:33792
	ds_read_b128 v[202:205], v161 offset:34816
	ds_read_b128 v[206:209], v161 offset:35840
	ds_read_b128 v[210:213], v161 offset:36864
	ds_read_b128 v[214:217], v161 offset:37888
	ds_read_b128 v[218:221], v161 offset:38912
	ds_read_b128 v[222:225], v161 offset:39936
	global_load_lds_dwordx4 v[234:235], off
	v_lshl_add_u64 v[234:235], s[40:41], 0, v[140:141]
	s_mov_b32 m0, s35
	s_nop 0
	global_load_lds_dwordx4 v[234:235], off
	s_waitcnt vmcnt(8)
	s_waitcnt lgkmcnt(0)
	s_setprio 1
	s_barrier
	v_mfma_f32_16x16x32_bf16 v[124:127], v[128:131], v[194:197], v[124:127]
	v_mfma_f32_16x16x32_bf16 v[120:123], v[164:167], v[194:197], v[120:123]
	v_mfma_f32_16x16x32_bf16 v[108:111], v[128:131], v[202:205], v[108:111]
	v_mfma_f32_16x16x32_bf16 v[104:107], v[164:167], v[202:205], v[104:107]
	v_mfma_f32_16x16x32_bf16 v[92:95], v[128:131], v[210:213], v[92:95]
	v_mfma_f32_16x16x32_bf16 v[88:91], v[164:167], v[210:213], v[88:91]
	v_mfma_f32_16x16x32_bf16 v[76:79], v[128:131], v[218:221], v[76:79]
	v_mfma_f32_16x16x32_bf16 v[72:75], v[164:167], v[218:221], v[72:75]
	v_mfma_f32_16x16x32_bf16 v[124:127], v[132:135], v[198:201], v[124:127]
	v_mfma_f32_16x16x32_bf16 v[120:123], v[168:171], v[198:201], v[120:123]
	v_mfma_f32_16x16x32_bf16 v[108:111], v[132:135], v[206:209], v[108:111]
	v_mfma_f32_16x16x32_bf16 v[104:107], v[168:171], v[206:209], v[104:107]
	v_mfma_f32_16x16x32_bf16 v[92:95], v[132:135], v[214:217], v[92:95]
	v_mfma_f32_16x16x32_bf16 v[88:91], v[168:171], v[214:217], v[88:91]
	v_mfma_f32_16x16x32_bf16 v[76:79], v[132:135], v[222:225], v[76:79]
	v_mfma_f32_16x16x32_bf16 v[72:75], v[168:171], v[222:225], v[72:75]
	s_setprio 0
	s_setprio 1
	v_mfma_f32_16x16x32_bf16 v[116:119], v[172:175], v[194:197], v[116:119]
	v_mfma_f32_16x16x32_bf16 v[112:115], v[180:183], v[194:197], v[112:115]
	v_mfma_f32_16x16x32_bf16 v[100:103], v[172:175], v[202:205], v[100:103]
	v_mfma_f32_16x16x32_bf16 v[96:99], v[180:183], v[202:205], v[96:99]
	v_mfma_f32_16x16x32_bf16 v[84:87], v[172:175], v[210:213], v[84:87]
	v_mfma_f32_16x16x32_bf16 v[80:83], v[180:183], v[210:213], v[80:83]
	v_mfma_f32_16x16x32_bf16 v[68:71], v[172:175], v[218:221], v[68:71]
	v_mfma_f32_16x16x32_bf16 v[64:67], v[180:183], v[218:221], v[64:67]
	v_mfma_f32_16x16x32_bf16 v[116:119], v[176:179], v[198:201], v[116:119]
	v_mfma_f32_16x16x32_bf16 v[112:115], v[190:193], v[198:201], v[112:115]
	v_mfma_f32_16x16x32_bf16 v[100:103], v[176:179], v[206:209], v[100:103]
	v_mfma_f32_16x16x32_bf16 v[96:99], v[190:193], v[206:209], v[96:99]
	v_mfma_f32_16x16x32_bf16 v[84:87], v[176:179], v[214:217], v[84:87]
	v_mfma_f32_16x16x32_bf16 v[80:83], v[190:193], v[214:217], v[80:83]
	v_mfma_f32_16x16x32_bf16 v[68:71], v[176:179], v[222:225], v[68:71]
	v_mfma_f32_16x16x32_bf16 v[64:67], v[190:193], v[222:225], v[64:67]
	s_barrier
; #define PG8_STAGE(bufoff, gbase, voff) do { _Pragma("unroll") for (int _i = 0; _i < 2; ++_i) \
;         __builtin_amdgcn_global_load_lds((const unsigned*)((const char*)(gbase) + (voff)[_i]), (PG8_LAS unsigned*)(lds + (bufoff) + ldsw + _i * 8192), 16, 0, 0); } while (0)
; #define PG8_LDA(dst, b, h) do { _Pragma("unroll") for (int m = 0; m < 4; ++m) _Pragma("unroll") for (int k = 0; k < 2; ++k) dst[m][k] = *(const PG8_LAS bf16x8*)(lds + PG8_SA(b, h) + aoff + m * 2048 + k * 1024); } while (0)
; #define PG8_MMA(ai, bj, At, Bt) do { __builtin_amdgcn_s_setprio(1); _Pragma("unroll") for (int m = 0; m < 4; ++m) _Pragma("unroll") for (int n = 0; n < 2; ++n) _Pragma("unroll") for (int k = 0; k < 2; ++k) \
;         acc[ai][bj][m][n] = __builtin_amdgcn_mfma_f32_16x16x32_bf16(Bt[n][k], At[m][k], acc[ai][bj][m][n], 0, 0, 0); __builtin_amdgcn_s_setprio(0); } while (0)
; #define PG8_WAIT_V(n) asm volatile("s_waitcnt vmcnt(" #n ")" ::: "memory")
; #define PG8_WAIT_L(n) asm volatile("s_waitcnt lgkmcnt(" #n ")" ::: "memory")
; #define PG8_BAR __builtin_amdgcn_s_barrier()
; #define PG8_SCHED __builtin_amdgcn_sched_barrier(0)
; template <class Epi, class Sched, bool ALIGN_EPI = false, bool SP2 = false>
; __device__ __forceinline__ void gemm_phase(PG8_LAS unsigned char* lds, const Gemm g, const Sched& S, const Epi& E) {
;     ...
;             PG8_LDA(At, 1, 1); PG8_STAGE(PG8_SB(1, 0), b3, voffB); PG8_STAGE(PG8_SB(1, 1), b3 + hstepB, voffB); PG8_STAGE(PG8_SA(1, 0), a3, voffA);
;             PG8_WAIT_V(8); PG8_WAIT_L(0); PG8_BAR; PG8_MMA(1, 0, At, B0); PG8_MMA(1, 1, At, B1); PG8_BAR; PG8_SCHED;
	s_setprio 0
	s_add_i32 s13, s13, s6
	v_lshl_add_u64 v[226:227], v[226:227], 0, s[54:55]
	s_mov_b32 m0, s13
	ds_read_b128 v[194:197], v161 offset:49152
	ds_read_b128 v[198:201], v161 offset:50176
	ds_read_b128 v[202:205], v161 offset:51200
	ds_read_b128 v[206:209], v161 offset:52224
	ds_read_b128 v[210:213], v161 offset:53248
	ds_read_b128 v[214:217], v161 offset:54272
	ds_read_b128 v[218:221], v161 offset:55296
	ds_read_b128 v[222:225], v161 offset:56320
	global_load_lds_dwordx4 v[226:227], off
	s_add_i32 m0, s13, 0x2000
	s_add_u32 s38, s38, 0x80080
	v_lshl_add_u64 v[226:227], v[228:229], 0, s[54:55]
	s_addc_u32 s39, s39, 0
	s_add_i32 s13, s33, s6
	global_load_lds_dwordx4 v[226:227], off
	v_lshl_add_u64 v[226:227], s[38:39], 0, v[138:139]
	s_mov_b32 m0, s13
	s_nop 0
	global_load_lds_dwordx4 v[226:227], off
	v_lshl_add_u64 v[226:227], s[38:39], 0, v[142:143]
	s_add_i32 m0, s13, 0x2000
	s_nop 0
	global_load_lds_dwordx4 v[226:227], off
	v_lshl_add_u64 v[226:227], v[230:231], 0, s[54:55]
	s_mov_b32 m0, s51
	s_nop 0
	global_load_lds_dwordx4 v[226:227], off
	v_lshl_add_u64 v[226:227], v[232:233], 0, s[54:55]
	s_mov_b32 m0, s68
	s_nop 0
	global_load_lds_dwordx4 v[226:227], off
	s_waitcnt vmcnt(8)
	s_waitcnt lgkmcnt(0)
	s_setprio 1
	s_barrier
	v_mfma_f32_16x16x32_bf16 v[60:63], v[128:131], v[194:197], v[60:63]
	v_mfma_f32_16x16x32_bf16 v[56:59], v[164:167], v[194:197], v[56:59]
	v_mfma_f32_16x16x32_bf16 v[44:47], v[128:131], v[202:205], v[44:47]
	v_mfma_f32_16x16x32_bf16 v[40:43], v[164:167], v[202:205], v[40:43]
	v_mfma_f32_16x16x32_bf16 v[28:31], v[128:131], v[210:213], v[28:31]
	v_mfma_f32_16x16x32_bf16 v[24:27], v[164:167], v[210:213], v[24:27]
	v_mfma_f32_16x16x32_bf16 v[12:15], v[128:131], v[218:221], v[12:15]
	v_mfma_f32_16x16x32_bf16 v[8:11], v[164:167], v[218:221], v[8:11]
	v_mfma_f32_16x16x32_bf16 v[60:63], v[132:135], v[198:201], v[60:63]
	v_mfma_f32_16x16x32_bf16 v[56:59], v[168:171], v[198:201], v[56:59]
	v_mfma_f32_16x16x32_bf16 v[44:47], v[132:135], v[206:209], v[44:47]
	v_mfma_f32_16x16x32_bf16 v[40:43], v[168:171], v[206:209], v[40:43]
	v_mfma_f32_16x16x32_bf16 v[28:31], v[132:135], v[214:217], v[28:31]
	v_mfma_f32_16x16x32_bf16 v[24:27], v[168:171], v[214:217], v[24:27]
	v_mfma_f32_16x16x32_bf16 v[12:15], v[132:135], v[222:225], v[12:15]
	v_mfma_f32_16x16x32_bf16 v[8:11], v[168:171], v[222:225], v[8:11]
	s_setprio 0
	s_setprio 1
	v_mfma_f32_16x16x32_bf16 v[52:55], v[172:175], v[194:197], v[52:55]
	v_mfma_f32_16x16x32_bf16 v[48:51], v[180:183], v[194:197], v[48:51]
	v_mfma_f32_16x16x32_bf16 v[36:39], v[172:175], v[202:205], v[36:39]
	v_mfma_f32_16x16x32_bf16 v[32:35], v[180:183], v[202:205], v[32:35]
	v_mfma_f32_16x16x32_bf16 v[20:23], v[172:175], v[210:213], v[20:23]
	v_mfma_f32_16x16x32_bf16 v[16:19], v[180:183], v[210:213], v[16:19]
	v_mfma_f32_16x16x32_bf16 v[4:7], v[172:175], v[218:221], v[4:7]
	v_mfma_f32_16x16x32_bf16 v[0:3], v[180:183], v[218:221], v[0:3]
	v_mfma_f32_16x16x32_bf16 v[52:55], v[176:179], v[198:201], v[52:55]
	v_mfma_f32_16x16x32_bf16 v[48:51], v[190:193], v[198:201], v[48:51]
	v_mfma_f32_16x16x32_bf16 v[36:39], v[176:179], v[206:209], v[36:39]
	v_mfma_f32_16x16x32_bf16 v[32:35], v[190:193], v[206:209], v[32:35]
	v_mfma_f32_16x16x32_bf16 v[20:23], v[176:179], v[214:217], v[20:23]
	v_mfma_f32_16x16x32_bf16 v[16:19], v[190:193], v[214:217], v[16:19]
	v_mfma_f32_16x16x32_bf16 v[4:7], v[176:179], v[222:225], v[4:7]
	v_mfma_f32_16x16x32_bf16 v[0:3], v[190:193], v[222:225], v[0:3]
	s_barrier
	s_setprio 0
	s_add_i32 s12, s12, 2
	s_add_u32 s20, s20, 0x100
	s_addc_u32 s21, s21, 0
	s_add_u32 s10, s10, 0x100
	s_addc_u32 s11, s11, 0
	s_cmp_gt_u32 s12, 29
	s_cbranch_scc1 .Lmy_peel_9_exit
	.p2alignl 6, 3212836864

; template <class Epi, class Sched, bool ALIGN_EPI = false, bool SP2 = false>
; __device__ __forceinline__ void gemm_phase(PG8_LAS unsigned char* lds, const Gemm g, const Sched& S, const Epi& E) {
;     ...
;         for (int t = 0; t < nt; t += 2) {
;             const bool last = (t == nt - 2);
;             const char* a1 = cA + (size_t)(t + 1) * kstA;
;             const char* a2 = last ? nA : cA + (size_t)(t + 2) * kstA; const char* b2 = last ? nB : cB + (size_t)(t + 2) * kstep;
.LBB0_2748:
	s_mov_b32 s1, 2
	s_mov_b64 s[62:63], 0x100
	v_mov_b64_e32 v[128:129], v[172:173]
	v_mov_b64_e32 v[130:131], v[170:171]
	.p2alignl 6, 3212836864

; #define PG8_STAGE(bufoff, gbase, voff) do { _Pragma("unroll") for (int _i = 0; _i < 2; ++_i) \
;         __builtin_amdgcn_global_load_lds((const unsigned*)((const char*)(gbase) + (voff)[_i]), (PG8_LAS unsigned*)(lds + (bufoff) + ldsw + _i * 8192), 16, 0, 0); } while (0)
; #define PG8_LDA(dst, b, h) do { _Pragma("unroll") for (int m = 0; m < 4; ++m) _Pragma("unroll") for (int k = 0; k < 2; ++k) dst[m][k] = *(const PG8_LAS bf16x8*)(lds + PG8_SA(b, h) + aoff + m * 2048 + k * 1024); } while (0)
; #define PG8_LDB(dst, b, h) do { _Pragma("unroll") for (int n = 0; n < 2; ++n) _Pragma("unroll") for (int k = 0; k < 2; ++k) dst[n][k] = *(const PG8_LAS bf16x8*)(lds + PG8_SB(b, h) + boff + n * 2048 + k * 1024); } while (0)
; #define PG8_WAIT_V(n) asm volatile("s_waitcnt vmcnt(" #n ")" ::: "memory")
; #define PG8_WAIT_L(n) asm volatile("s_waitcnt lgkmcnt(" #n ")" ::: "memory")
; template <class Epi, class Sched, bool ALIGN_EPI = false, bool SP2 = false>
; __device__ __forceinline__ void gemm_phase(PG8_LAS unsigned char* lds, const Gemm g, const Sched& S, const Epi& E) {
;     ...
;         const bool has_next = S.next(ui + 1, nxt);
;         const char* nA = has_next ? (const char*)g.A + (size_t)nxt.pm * tstepA + (size_t)nxt.z * g.azs + (size_t)(nxt.k0 >> 6) * kstA : cA; const char* nB = has_next ? (const char*)g.Bt + (size_t)nxt.pn * tstepB + (size_t)nxt.z * g.bzs + (size_t)nxt.k0 * 2 : cB;
;         const int nt = cur.nt;
;         for (int t = 0; t < nt; t += 2) {
;             const bool last = (t == nt - 2);
;             const char* a1 = cA + (size_t)(t + 1) * kstA;
;             const char* a2 = last ? nA : cA + (size_t)(t + 2) * kstA; const char* b2 = last ? nB : cB + (size_t)(t + 2) * kstep;
;             const char* a3 = a2 + kstA; const char* b3 = b2 + kstep;
;             if (last && has_next) S.a_ready(nxt);
;             if constexpr (SP2) {
;             PG8_LDB(B0, 0, 0); PG8_LDB(B1, 0, 1); PG8_SCHED; PG8_LDA(At, 0, 0); PG8_STAGE(PG8_SA(1, 1), a1 + hstepA, voffA);
;             PG8_WAIT_V(8); PG8_WAIT_L(0); PG8_BAR; PG8_MMA(0, 0, At, B0); PG8_MMA(0, 1, At, B1); PG8_BAR; PG8_SCHED;
;             PG8_LDA(At, 0, 1); PG8_STAGE(PG8_SB(0, 0), b2, voffB); PG8_STAGE(PG8_SB(0, 1), b2 + hstepB, voffB); PG8_STAGE(PG8_SA(0, 0), a2, voffA);
;             PG8_WAIT_V(8); PG8_WAIT_L(0); PG8_BAR; PG8_MMA(1, 0, At, B0); PG8_MMA(1, 1, At, B1); PG8_BAR; PG8_SCHED;
.LBB0_3057:
	s_ashr_i32 s23, s22, 31
	s_lshl_b64 s[4:5], s[22:23], 20
	v_readlane_b32 s12, v254, 41
	v_readlane_b32 s13, v254, 42
	s_add_u32 s24, s12, s4
	s_addc_u32 s25, s13, s5
	s_and_b64 s[4:5], s[36:37], exec
	s_cselect_b32 s4, s25, s41
	s_cselect_b32 s5, s24, s40
	s_ashr_i32 s21, s20, 31
	s_lshl_b64 s[12:13], s[20:21], 20
	s_add_u32 s30, s3, s12
	s_addc_u32 s31, s6, s13
	s_and_b64 s[12:13], s[36:37], exec
	s_cselect_b32 s12, s31, s43
	s_cselect_b32 s13, s30, s42
	s_add_u32 s40, s40, 0x80080
	s_addc_u32 s41, s41, 0
	s_add_u32 s21, s42, 0x100
	s_addc_u32 s23, s43, 0
	s_mov_b32 s35, -2
	ds_read_b128 v[156:159], v152
	ds_read_b128 v[160:163], v152 offset:1024
	ds_read_b128 v[164:167], v152 offset:2048
	ds_read_b128 v[168:171], v152 offset:3072
	ds_read_b128 v[172:175], v153
	ds_read_b128 v[176:179], v153 offset:1024
	ds_read_b128 v[180:183], v153 offset:2048
	ds_read_b128 v[190:193], v153 offset:3072
	s_add_u32 s42, s40, 0xfff80080
	s_addc_u32 s43, s41, -1
	s_cmp_eq_u32 s35, 28
	s_cselect_b32 s45, s4, s43
	s_cselect_b32 s44, s5, s42
	s_cselect_b32 s43, s12, s23
	s_cselect_b32 s42, s13, s21
	v_lshl_add_u64 v[226:227], s[40:41], 0, v[142:143]
	s_add_i32 m0, s8, 0xc000
	ds_read_b128 v[194:197], v154
	ds_read_b128 v[198:201], v154 offset:1024
	ds_read_b128 v[202:205], v154 offset:2048
	ds_read_b128 v[206:209], v154 offset:3072
	ds_read_b128 v[210:213], v154 offset:4096
	ds_read_b128 v[214:217], v154 offset:5120
	ds_read_b128 v[218:221], v154 offset:6144
	ds_read_b128 v[222:225], v154 offset:7168
	global_load_lds_dwordx4 v[226:227], off
	v_lshl_add_u64 v[226:227], s[40:41], 0, v[144:145]
	s_add_i32 m0, s8, 0xe000
	s_nop 0
	global_load_lds_dwordx4 v[226:227], off
	s_waitcnt vmcnt(8)
	s_waitcnt lgkmcnt(0)
	s_setprio 1
	s_barrier
	v_mfma_f32_16x16x32_bf16 v[124:127], v[156:159], v[194:197], 0
	v_mfma_f32_16x16x32_bf16 v[120:123], v[164:167], v[194:197], 0
	v_mfma_f32_16x16x32_bf16 v[108:111], v[156:159], v[202:205], 0
	v_mfma_f32_16x16x32_bf16 v[104:107], v[164:167], v[202:205], 0
	v_mfma_f32_16x16x32_bf16 v[92:95], v[156:159], v[210:213], 0
	v_mfma_f32_16x16x32_bf16 v[88:91], v[164:167], v[210:213], 0
	v_mfma_f32_16x16x32_bf16 v[76:79], v[156:159], v[218:221], 0
	v_mfma_f32_16x16x32_bf16 v[72:75], v[164:167], v[218:221], 0
	v_mfma_f32_16x16x32_bf16 v[124:127], v[160:163], v[198:201], v[124:127]
	v_mfma_f32_16x16x32_bf16 v[120:123], v[168:171], v[198:201], v[120:123]
	v_mfma_f32_16x16x32_bf16 v[108:111], v[160:163], v[206:209], v[108:111]
	v_mfma_f32_16x16x32_bf16 v[104:107], v[168:171], v[206:209], v[104:107]
	v_mfma_f32_16x16x32_bf16 v[92:95], v[160:163], v[214:217], v[92:95]
	v_mfma_f32_16x16x32_bf16 v[88:91], v[168:171], v[214:217], v[88:91]
	v_mfma_f32_16x16x32_bf16 v[76:79], v[160:163], v[222:225], v[76:79]
	v_mfma_f32_16x16x32_bf16 v[72:75], v[168:171], v[222:225], v[72:75]
	s_setprio 0
	s_setprio 1
	v_mfma_f32_16x16x32_bf16 v[116:119], v[172:175], v[194:197], 0
	v_mfma_f32_16x16x32_bf16 v[112:115], v[180:183], v[194:197], 0
	v_mfma_f32_16x16x32_bf16 v[100:103], v[172:175], v[202:205], 0
	v_mfma_f32_16x16x32_bf16 v[96:99], v[180:183], v[202:205], 0
	v_mfma_f32_16x16x32_bf16 v[84:87], v[172:175], v[210:213], 0
	v_mfma_f32_16x16x32_bf16 v[80:83], v[180:183], v[210:213], 0
	v_mfma_f32_16x16x32_bf16 v[68:71], v[172:175], v[218:221], 0
	v_mfma_f32_16x16x32_bf16 v[64:67], v[180:183], v[218:221], 0
	v_mfma_f32_16x16x32_bf16 v[116:119], v[176:179], v[198:201], v[116:119]
	v_mfma_f32_16x16x32_bf16 v[112:115], v[190:193], v[198:201], v[112:115]
	v_mfma_f32_16x16x32_bf16 v[100:103], v[176:179], v[206:209], v[100:103]
	v_mfma_f32_16x16x32_bf16 v[96:99], v[190:193], v[206:209], v[96:99]
	v_mfma_f32_16x16x32_bf16 v[84:87], v[176:179], v[214:217], v[84:87]
	v_mfma_f32_16x16x32_bf16 v[80:83], v[190:193], v[214:217], v[80:83]
	v_mfma_f32_16x16x32_bf16 v[68:71], v[176:179], v[222:225], v[68:71]
	v_mfma_f32_16x16x32_bf16 v[64:67], v[190:193], v[222:225], v[64:67]
	s_barrier
	s_setprio 0
	s_add_i32 s53, s50, s7
	v_lshl_add_u64 v[226:227], s[42:43], 0, v[130:131]
	s_mov_b32 m0, s53
	ds_read_b128 v[194:197], v154 offset:16384
	ds_read_b128 v[198:201], v154 offset:17408
	ds_read_b128 v[202:205], v154 offset:18432
	ds_read_b128 v[206:209], v154 offset:19456
	ds_read_b128 v[210:213], v154 offset:20480
	ds_read_b128 v[214:217], v154 offset:21504
	ds_read_b128 v[218:221], v154 offset:22528
	ds_read_b128 v[222:225], v154 offset:23552
	global_load_lds_dwordx4 v[226:227], off
	s_add_i32 m0, s53, 0x2000
	s_add_u32 s54, s42, 0x80000
	v_lshl_add_u64 v[228:229], s[42:43], 0, v[134:135]
	s_addc_u32 s55, s43, 0
	s_add_i32 s53, s51, s7
	global_load_lds_dwordx4 v[228:229], off
	v_lshl_add_u64 v[230:231], s[54:55], 0, v[130:131]
	s_mov_b32 m0, s53
	v_lshl_add_u64 v[232:233], s[44:45], 0, v[132:133]
	global_load_lds_dwordx4 v[230:231], off
	v_lshl_add_u64 v[230:231], s[54:55], 0, v[134:135]
	s_add_i32 m0, s53, 0x2000
	s_nop 0
	global_load_lds_dwordx4 v[230:231], off
	v_lshl_add_u64 v[230:231], s[44:45], 0, v[128:129]
	s_mov_b32 m0, s8
	s_nop 0
	global_load_lds_dwordx4 v[230:231], off
	s_mov_b32 m0, s9
	s_nop 0
	global_load_lds_dwordx4 v[232:233], off
	s_waitcnt vmcnt(8)
	s_waitcnt lgkmcnt(0)
	s_setprio 1
	s_barrier
; #define PG8_STAGE(bufoff, gbase, voff) do { _Pragma("unroll") for (int _i = 0; _i < 2; ++_i) \
;         __builtin_amdgcn_global_load_lds((const unsigned*)((const char*)(gbase) + (voff)[_i]), (PG8_LAS unsigned*)(lds + (bufoff) + ldsw + _i * 8192), 16, 0, 0); } while (0)
; #define PG8_LDA(dst, b, h) do { _Pragma("unroll") for (int m = 0; m < 4; ++m) _Pragma("unroll") for (int k = 0; k < 2; ++k) dst[m][k] = *(const PG8_LAS bf16x8*)(lds + PG8_SA(b, h) + aoff + m * 2048 + k * 1024); } while (0)
; #define PG8_LDB(dst, b, h) do { _Pragma("unroll") for (int n = 0; n < 2; ++n) _Pragma("unroll") for (int k = 0; k < 2; ++k) dst[n][k] = *(const PG8_LAS bf16x8*)(lds + PG8_SB(b, h) + boff + n * 2048 + k * 1024); } while (0)
; #define PG8_MMA(ai, bj, At, Bt) do { __builtin_amdgcn_s_setprio(1); _Pragma("unroll") for (int m = 0; m < 4; ++m) _Pragma("unroll") for (int n = 0; n < 2; ++n) _Pragma("unroll") for (int k = 0; k < 2; ++k) \
;         acc[ai][bj][m][n] = __builtin_amdgcn_mfma_f32_16x16x32_bf16(Bt[n][k], At[m][k], acc[ai][bj][m][n], 0, 0, 0); __builtin_amdgcn_s_setprio(0); } while (0)
; #define PG8_WAIT_V(n) asm volatile("s_waitcnt vmcnt(" #n ")" ::: "memory")
; #define PG8_WAIT_L(n) asm volatile("s_waitcnt lgkmcnt(" #n ")" ::: "memory")
; #define PG8_BAR __builtin_amdgcn_s_barrier()
; #define PG8_SCHED __builtin_amdgcn_sched_barrier(0)
; template <class Epi, class Sched, bool ALIGN_EPI = false, bool SP2 = false>
; __device__ __forceinline__ void gemm_phase(PG8_LAS unsigned char* lds, const Gemm g, const Sched& S, const Epi& E) {
;     ...
;             PG8_WAIT_V(8); PG8_WAIT_L(0); PG8_BAR; PG8_MMA(1, 0, At, B0); PG8_MMA(1, 1, At, B1); PG8_BAR; PG8_SCHED;
;             PG8_LDB(B0, 1, 0); PG8_LDB(B1, 1, 1); PG8_SCHED; PG8_LDA(At, 1, 0); PG8_STAGE(PG8_SA(0, 1), a2 + hstepA, voffA);
;             PG8_WAIT_V(8); PG8_WAIT_L(0); PG8_BAR; PG8_MMA(0, 0, At, B0); PG8_MMA(0, 1, At, B1); PG8_BAR; PG8_SCHED;
	v_mfma_f32_16x16x32_bf16 v[60:63], v[156:159], v[194:197], 0
	v_mfma_f32_16x16x32_bf16 v[56:59], v[164:167], v[194:197], 0
	v_mfma_f32_16x16x32_bf16 v[44:47], v[156:159], v[202:205], 0
	v_mfma_f32_16x16x32_bf16 v[40:43], v[164:167], v[202:205], 0
	v_mfma_f32_16x16x32_bf16 v[28:31], v[156:159], v[210:213], 0
	v_mfma_f32_16x16x32_bf16 v[24:27], v[164:167], v[210:213], 0
	v_mfma_f32_16x16x32_bf16 v[12:15], v[156:159], v[218:221], 0
	v_mfma_f32_16x16x32_bf16 v[8:11], v[164:167], v[218:221], 0
	v_mfma_f32_16x16x32_bf16 v[60:63], v[160:163], v[198:201], v[60:63]
	v_mfma_f32_16x16x32_bf16 v[56:59], v[168:171], v[198:201], v[56:59]
	v_mfma_f32_16x16x32_bf16 v[44:47], v[160:163], v[206:209], v[44:47]
	v_mfma_f32_16x16x32_bf16 v[40:43], v[168:171], v[206:209], v[40:43]
	v_mfma_f32_16x16x32_bf16 v[28:31], v[160:163], v[214:217], v[28:31]
	v_mfma_f32_16x16x32_bf16 v[24:27], v[168:171], v[214:217], v[24:27]
	v_mfma_f32_16x16x32_bf16 v[12:15], v[160:163], v[222:225], v[12:15]
	v_mfma_f32_16x16x32_bf16 v[8:11], v[168:171], v[222:225], v[8:11]
	s_setprio 0
	s_setprio 1
	v_mfma_f32_16x16x32_bf16 v[52:55], v[172:175], v[194:197], 0
	v_mfma_f32_16x16x32_bf16 v[48:51], v[180:183], v[194:197], 0
	v_mfma_f32_16x16x32_bf16 v[36:39], v[172:175], v[202:205], 0
	v_mfma_f32_16x16x32_bf16 v[32:35], v[180:183], v[202:205], 0
	v_mfma_f32_16x16x32_bf16 v[20:23], v[172:175], v[210:213], 0
	v_mfma_f32_16x16x32_bf16 v[16:19], v[180:183], v[210:213], 0
	v_mfma_f32_16x16x32_bf16 v[4:7], v[172:175], v[218:221], 0
	v_mfma_f32_16x16x32_bf16 v[0:3], v[180:183], v[218:221], 0
	v_mfma_f32_16x16x32_bf16 v[52:55], v[176:179], v[198:201], v[52:55]
	v_mfma_f32_16x16x32_bf16 v[48:51], v[190:193], v[198:201], v[48:51]
	v_mfma_f32_16x16x32_bf16 v[36:39], v[176:179], v[206:209], v[36:39]
	v_mfma_f32_16x16x32_bf16 v[32:35], v[190:193], v[206:209], v[32:35]
	v_mfma_f32_16x16x32_bf16 v[20:23], v[176:179], v[214:217], v[20:23]
	v_mfma_f32_16x16x32_bf16 v[16:19], v[190:193], v[214:217], v[16:19]
	v_mfma_f32_16x16x32_bf16 v[4:7], v[176:179], v[222:225], v[4:7]
	v_mfma_f32_16x16x32_bf16 v[0:3], v[190:193], v[222:225], v[0:3]
	s_barrier
	s_setprio 0
	s_add_i32 s53, 0, 0x18000
	v_add_u32_e32 v155, s53, v150
	s_add_i32 s54, 0, 0x1c000
	ds_read_b128 v[156:159], v155
	ds_read_b128 v[160:163], v155 offset:1024
	ds_read_b128 v[164:167], v155 offset:2048
	ds_read_b128 v[168:171], v155 offset:3072
	v_add_u32_e32 v155, s54, v150
	ds_read_b128 v[172:175], v155
	ds_read_b128 v[176:179], v155 offset:1024
	ds_read_b128 v[180:183], v155 offset:2048
	ds_read_b128 v[190:193], v155 offset:3072
	s_add_u32 s44, s44, 0x80000
	s_addc_u32 s45, s45, 0
	s_mov_b32 m0, s10
	v_lshl_add_u64 v[234:235], s[44:45], 0, v[128:129]
	ds_read_b128 v[194:197], v154 offset:32768
	ds_read_b128 v[198:201], v154 offset:33792
	ds_read_b128 v[202:205], v154 offset:34816
	ds_read_b128 v[206:209], v154 offset:35840
	ds_read_b128 v[210:213], v154 offset:36864
	ds_read_b128 v[214:217], v154 offset:37888
	ds_read_b128 v[218:221], v154 offset:38912
	ds_read_b128 v[222:225], v154 offset:39936
	global_load_lds_dwordx4 v[234:235], off
	v_lshl_add_u64 v[234:235], s[44:45], 0, v[132:133]
	s_mov_b32 m0, s11
	s_nop 0
	global_load_lds_dwordx4 v[234:235], off
	s_waitcnt vmcnt(8)
	s_waitcnt lgkmcnt(0)
	s_setprio 1
	s_barrier
	v_mfma_f32_16x16x32_bf16 v[124:127], v[156:159], v[194:197], v[124:127]
	v_mfma_f32_16x16x32_bf16 v[120:123], v[164:167], v[194:197], v[120:123]
	v_mfma_f32_16x16x32_bf16 v[108:111], v[156:159], v[202:205], v[108:111]
	v_mfma_f32_16x16x32_bf16 v[104:107], v[164:167], v[202:205], v[104:107]
	v_mfma_f32_16x16x32_bf16 v[92:95], v[156:159], v[210:213], v[92:95]
	v_mfma_f32_16x16x32_bf16 v[88:91], v[164:167], v[210:213], v[88:91]
	v_mfma_f32_16x16x32_bf16 v[76:79], v[156:159], v[218:221], v[76:79]
	v_mfma_f32_16x16x32_bf16 v[72:75], v[164:167], v[218:221], v[72:75]
	v_mfma_f32_16x16x32_bf16 v[124:127], v[160:163], v[198:201], v[124:127]
	v_mfma_f32_16x16x32_bf16 v[120:123], v[168:171], v[198:201], v[120:123]
	v_mfma_f32_16x16x32_bf16 v[108:111], v[160:163], v[206:209], v[108:111]
	v_mfma_f32_16x16x32_bf16 v[104:107], v[168:171], v[206:209], v[104:107]
	v_mfma_f32_16x16x32_bf16 v[92:95], v[160:163], v[214:217], v[92:95]
	v_mfma_f32_16x16x32_bf16 v[88:91], v[168:171], v[214:217], v[88:91]
	v_mfma_f32_16x16x32_bf16 v[76:79], v[160:163], v[222:225], v[76:79]
	v_mfma_f32_16x16x32_bf16 v[72:75], v[168:171], v[222:225], v[72:75]
	s_setprio 0
	s_setprio 1
	v_mfma_f32_16x16x32_bf16 v[116:119], v[172:175], v[194:197], v[116:119]
	v_mfma_f32_16x16x32_bf16 v[112:115], v[180:183], v[194:197], v[112:115]
	v_mfma_f32_16x16x32_bf16 v[100:103], v[172:175], v[202:205], v[100:103]
	v_mfma_f32_16x16x32_bf16 v[96:99], v[180:183], v[202:205], v[96:99]
	v_mfma_f32_16x16x32_bf16 v[84:87], v[172:175], v[210:213], v[84:87]
	v_mfma_f32_16x16x32_bf16 v[80:83], v[180:183], v[210:213], v[80:83]
	v_mfma_f32_16x16x32_bf16 v[68:71], v[172:175], v[218:221], v[68:71]
	v_mfma_f32_16x16x32_bf16 v[64:67], v[180:183], v[218:221], v[64:67]
	v_mfma_f32_16x16x32_bf16 v[116:119], v[176:179], v[198:201], v[116:119]
	v_mfma_f32_16x16x32_bf16 v[112:115], v[190:193], v[198:201], v[112:115]
	v_mfma_f32_16x16x32_bf16 v[100:103], v[176:179], v[206:209], v[100:103]
	v_mfma_f32_16x16x32_bf16 v[96:99], v[190:193], v[206:209], v[96:99]
	v_mfma_f32_16x16x32_bf16 v[84:87], v[176:179], v[214:217], v[84:87]
	v_mfma_f32_16x16x32_bf16 v[80:83], v[190:193], v[214:217], v[80:83]
	v_mfma_f32_16x16x32_bf16 v[68:71], v[176:179], v[222:225], v[68:71]
	v_mfma_f32_16x16x32_bf16 v[64:67], v[190:193], v[222:225], v[64:67]
	s_barrier
; #define PG8_STAGE(bufoff, gbase, voff) do { _Pragma("unroll") for (int _i = 0; _i < 2; ++_i) \
;         __builtin_amdgcn_global_load_lds((const unsigned*)((const char*)(gbase) + (voff)[_i]), (PG8_LAS unsigned*)(lds + (bufoff) + ldsw + _i * 8192), 16, 0, 0); } while (0)
; #define PG8_LDA(dst, b, h) do { _Pragma("unroll") for (int m = 0; m < 4; ++m) _Pragma("unroll") for (int k = 0; k < 2; ++k) dst[m][k] = *(const PG8_LAS bf16x8*)(lds + PG8_SA(b, h) + aoff + m * 2048 + k * 1024); } while (0)
; #define PG8_MMA(ai, bj, At, Bt) do { __builtin_amdgcn_s_setprio(1); _Pragma("unroll") for (int m = 0; m < 4; ++m) _Pragma("unroll") for (int n = 0; n < 2; ++n) _Pragma("unroll") for (int k = 0; k < 2; ++k) \
;         acc[ai][bj][m][n] = __builtin_amdgcn_mfma_f32_16x16x32_bf16(Bt[n][k], At[m][k], acc[ai][bj][m][n], 0, 0, 0); __builtin_amdgcn_s_setprio(0); } while (0)
; #define PG8_WAIT_V(n) asm volatile("s_waitcnt vmcnt(" #n ")" ::: "memory")
; #define PG8_WAIT_L(n) asm volatile("s_waitcnt lgkmcnt(" #n ")" ::: "memory")
; #define PG8_BAR __builtin_amdgcn_s_barrier()
; #define PG8_SCHED __builtin_amdgcn_sched_barrier(0)
; template <class Epi, class Sched, bool ALIGN_EPI = false, bool SP2 = false>
; __device__ __forceinline__ void gemm_phase(PG8_LAS unsigned char* lds, const Gemm g, const Sched& S, const Epi& E) {
;     ...
;             PG8_LDA(At, 1, 1); PG8_STAGE(PG8_SB(1, 0), b3, voffB); PG8_STAGE(PG8_SB(1, 1), b3 + hstepB, voffB); PG8_STAGE(PG8_SA(1, 0), a3, voffA);
;             PG8_WAIT_V(8); PG8_WAIT_L(0); PG8_BAR; PG8_MMA(1, 0, At, B0); PG8_MMA(1, 1, At, B1); PG8_BAR; PG8_SCHED;
	s_setprio 0
	s_add_i32 s44, s53, s7
	v_lshl_add_u64 v[226:227], v[226:227], 0, s[16:17]
	s_mov_b32 m0, s44
	ds_read_b128 v[194:197], v154 offset:49152
	ds_read_b128 v[198:201], v154 offset:50176
	ds_read_b128 v[202:205], v154 offset:51200
	ds_read_b128 v[206:209], v154 offset:52224
	ds_read_b128 v[210:213], v154 offset:53248
	ds_read_b128 v[214:217], v154 offset:54272
	ds_read_b128 v[218:221], v154 offset:55296
	ds_read_b128 v[222:225], v154 offset:56320
	global_load_lds_dwordx4 v[226:227], off
	s_add_i32 m0, s44, 0x2000
	s_add_u32 s42, s42, 0x80080
	v_lshl_add_u64 v[226:227], v[228:229], 0, s[16:17]
	s_addc_u32 s43, s43, 0
	s_add_i32 s44, s54, s7
	global_load_lds_dwordx4 v[226:227], off
	v_lshl_add_u64 v[226:227], s[42:43], 0, v[130:131]
	s_mov_b32 m0, s44
	s_nop 0
	global_load_lds_dwordx4 v[226:227], off
	v_lshl_add_u64 v[226:227], s[42:43], 0, v[134:135]
	s_add_i32 m0, s44, 0x2000
	s_nop 0
	global_load_lds_dwordx4 v[226:227], off
	v_lshl_add_u64 v[226:227], v[230:231], 0, s[16:17]
	s_mov_b32 m0, s48
	s_nop 0
	global_load_lds_dwordx4 v[226:227], off
	v_lshl_add_u64 v[226:227], v[232:233], 0, s[16:17]
	s_mov_b32 m0, s49
	s_nop 0
	global_load_lds_dwordx4 v[226:227], off
	s_waitcnt vmcnt(8)
	s_waitcnt lgkmcnt(0)
	s_setprio 1
	s_barrier
	v_mfma_f32_16x16x32_bf16 v[60:63], v[156:159], v[194:197], v[60:63]
	v_mfma_f32_16x16x32_bf16 v[56:59], v[164:167], v[194:197], v[56:59]
	v_mfma_f32_16x16x32_bf16 v[44:47], v[156:159], v[202:205], v[44:47]
	v_mfma_f32_16x16x32_bf16 v[40:43], v[164:167], v[202:205], v[40:43]
	v_mfma_f32_16x16x32_bf16 v[28:31], v[156:159], v[210:213], v[28:31]
	v_mfma_f32_16x16x32_bf16 v[24:27], v[164:167], v[210:213], v[24:27]
	v_mfma_f32_16x16x32_bf16 v[12:15], v[156:159], v[218:221], v[12:15]
	v_mfma_f32_16x16x32_bf16 v[8:11], v[164:167], v[218:221], v[8:11]
	v_mfma_f32_16x16x32_bf16 v[60:63], v[160:163], v[198:201], v[60:63]
	v_mfma_f32_16x16x32_bf16 v[56:59], v[168:171], v[198:201], v[56:59]
	v_mfma_f32_16x16x32_bf16 v[44:47], v[160:163], v[206:209], v[44:47]
	v_mfma_f32_16x16x32_bf16 v[40:43], v[168:171], v[206:209], v[40:43]
	v_mfma_f32_16x16x32_bf16 v[28:31], v[160:163], v[214:217], v[28:31]
	v_mfma_f32_16x16x32_bf16 v[24:27], v[168:171], v[214:217], v[24:27]
	v_mfma_f32_16x16x32_bf16 v[12:15], v[160:163], v[222:225], v[12:15]
	v_mfma_f32_16x16x32_bf16 v[8:11], v[168:171], v[222:225], v[8:11]
	s_setprio 0
	s_setprio 1
	v_mfma_f32_16x16x32_bf16 v[52:55], v[172:175], v[194:197], v[52:55]
	v_mfma_f32_16x16x32_bf16 v[48:51], v[180:183], v[194:197], v[48:51]
	v_mfma_f32_16x16x32_bf16 v[36:39], v[172:175], v[202:205], v[36:39]
	v_mfma_f32_16x16x32_bf16 v[32:35], v[180:183], v[202:205], v[32:35]
	v_mfma_f32_16x16x32_bf16 v[20:23], v[172:175], v[210:213], v[20:23]
	v_mfma_f32_16x16x32_bf16 v[16:19], v[180:183], v[210:213], v[16:19]
	v_mfma_f32_16x16x32_bf16 v[4:7], v[172:175], v[218:221], v[4:7]
	v_mfma_f32_16x16x32_bf16 v[0:3], v[180:183], v[218:221], v[0:3]
	v_mfma_f32_16x16x32_bf16 v[52:55], v[176:179], v[198:201], v[52:55]
	v_mfma_f32_16x16x32_bf16 v[48:51], v[190:193], v[198:201], v[48:51]
	v_mfma_f32_16x16x32_bf16 v[36:39], v[176:179], v[206:209], v[36:39]
	v_mfma_f32_16x16x32_bf16 v[32:35], v[190:193], v[206:209], v[32:35]
	v_mfma_f32_16x16x32_bf16 v[20:23], v[176:179], v[214:217], v[20:23]
	v_mfma_f32_16x16x32_bf16 v[16:19], v[190:193], v[214:217], v[16:19]
	v_mfma_f32_16x16x32_bf16 v[4:7], v[176:179], v[222:225], v[4:7]
	v_mfma_f32_16x16x32_bf16 v[0:3], v[190:193], v[222:225], v[0:3]
	s_barrier
	s_setprio 0
	s_add_i32 s35, s35, 2
	s_add_u32 s40, s40, 0x100
	s_addc_u32 s41, s41, 0
	s_add_u32 s21, s21, 0x100
	s_addc_u32 s23, s23, 0
	s_cmp_gt_u32 s35, 29
	s_cbranch_scc1 .Lmy_peel_11_exit
	.p2alignl 6, 3212836864

; template <class Epi, class Sched, bool ALIGN_EPI = false, bool SP2 = false>
; __device__ __forceinline__ void gemm_phase(PG8_LAS unsigned char* lds, const Gemm g, const Sched& S, const Epi& E) {
;     ...
;     for (;;) {
;         const bool has_next = S.next(ui + 1, nxt);
;         const char* nA = has_next ? (const char*)g.A + (size_t)nxt.pm * tstepA + (size_t)nxt.z * g.azs + (size_t)(nxt.k0 >> 6) * kstA : cA; const char* nB = has_next ? (const char*)g.Bt + (size_t)nxt.pn * tstepB + (size_t)nxt.z * g.bzs + (size_t)nxt.k0 * 2 : cB;
;         const int nt = cur.nt;
;         for (int t = 0; t < nt; t += 2) {
;             const bool last = (t == nt - 2);
;             const char* a1 = cA + (size_t)(t + 1) * kstA;
;             const char* a2 = last ? nA : cA + (size_t)(t + 2) * kstA; const char* b2 = last ? nB : cB + (size_t)(t + 2) * kstep;
;             const char* a3 = a2 + kstA; const char* b3 = b2 + kstep;
.LBB0_3146:
	s_add_u32 s1, s22, 0x100
	s_addc_u32 s4, s23, 0
	s_mov_b32 s5, 2
	s_mov_b64 s[46:47], 0x10000
	v_mov_b64_e32 v[160:161], v[156:157]
	v_mov_b64_e32 v[162:163], v[154:155]
	.p2alignl 6, 3212836864
